# K-loop: phase-1 next-unit pointer-select SALU group sunk from the load segment into MFMA cadence gaps (on top of v16)
# speedup vs baseline: 1.0098x; 1.0012x over previous
.LBB0_92:
	ds_read_b128 v[146:149], v143
	ds_read_b128 v[150:153], v143 offset:1024
	ds_read_b128 v[154:157], v143 offset:2048
	ds_read_b128 v[158:161], v143 offset:3072
	ds_read_b128 v[162:165], v144
	ds_read_b128 v[166:169], v144 offset:1024
	ds_read_b128 v[170:173], v144 offset:2048
	ds_read_b128 v[178:181], v144 offset:3072
	ds_read_b128 v[182:185], v145
	ds_read_b128 v[186:189], v145 offset:1024
	ds_read_b128 v[190:193], v145 offset:2048
	ds_read_b128 v[194:197], v145 offset:3072
	ds_read_b128 v[198:201], v145 offset:4096
	ds_read_b128 v[206:209], v145 offset:5120
	ds_read_b128 v[210:213], v145 offset:6144
	ds_read_b128 v[214:217], v145 offset:7168
	s_add_i32 m0, s27, 0xc000
	v_lshl_add_u64 v[174:175], s[28:29], 0, v[136:137]
	global_load_lds_dwordx4 v[174:175], off
	s_add_i32 m0, s27, 0xe000
	v_lshl_add_u64 v[174:175], s[28:29], 0, v[138:139]
	global_load_lds_dwordx4 v[174:175], off
	s_waitcnt vmcnt(8) lgkmcnt(0)
	s_setprio 1
	s_barrier
	v_mfma_f32_16x16x32_bf16 v[124:127], v[146:149], v[182:185], v[124:127]
	v_mfma_f32_16x16x32_bf16 v[120:123], v[154:157], v[182:185], v[120:123]
	v_mfma_f32_16x16x32_bf16 v[116:119], v[146:149], v[190:193], v[116:119]
	s_add_u32 s0, s28, 0xfff80080
	v_mfma_f32_16x16x32_bf16 v[108:111], v[154:157], v[190:193], v[108:111]
	s_addc_u32 s1, s29, -1
	v_mfma_f32_16x16x32_bf16 v[100:103], v[146:149], v[198:201], v[100:103]
	s_cmp_eq_u32 s68, 28
	v_mfma_f32_16x16x32_bf16 v[92:95], v[154:157], v[198:201], v[92:95]
	s_cselect_b32 s35, s13, s1
	v_mfma_f32_16x16x32_bf16 v[84:87], v[146:149], v[210:213], v[84:87]
	s_cselect_b32 s34, s63, s0
	v_mfma_f32_16x16x32_bf16 v[76:79], v[154:157], v[210:213], v[76:79]
	s_cselect_b32 s31, s64, s67
	v_mfma_f32_16x16x32_bf16 v[124:127], v[150:153], v[186:189], v[124:127]
	s_cselect_b32 s30, s65, s66
	v_mfma_f32_16x16x32_bf16 v[120:123], v[158:161], v[186:189], v[120:123]
	v_mfma_f32_16x16x32_bf16 v[116:119], v[150:153], v[194:197], v[116:119]
	v_mfma_f32_16x16x32_bf16 v[108:111], v[158:161], v[194:197], v[108:111]
	v_mfma_f32_16x16x32_bf16 v[100:103], v[150:153], v[206:209], v[100:103]
	v_mfma_f32_16x16x32_bf16 v[92:95], v[158:161], v[206:209], v[92:95]
	v_mfma_f32_16x16x32_bf16 v[84:87], v[150:153], v[214:217], v[84:87]
	v_mfma_f32_16x16x32_bf16 v[76:79], v[158:161], v[214:217], v[76:79]
	v_mfma_f32_16x16x32_bf16 v[112:115], v[162:165], v[182:185], v[112:115]
	v_mfma_f32_16x16x32_bf16 v[104:107], v[170:173], v[182:185], v[104:107]
	v_mfma_f32_16x16x32_bf16 v[96:99], v[162:165], v[190:193], v[96:99]
	v_mfma_f32_16x16x32_bf16 v[88:91], v[170:173], v[190:193], v[88:91]
	v_mfma_f32_16x16x32_bf16 v[80:83], v[162:165], v[198:201], v[80:83]
	v_mfma_f32_16x16x32_bf16 v[72:75], v[170:173], v[198:201], v[72:75]
	v_mfma_f32_16x16x32_bf16 v[68:71], v[162:165], v[210:213], v[68:71]
	v_mfma_f32_16x16x32_bf16 v[64:67], v[170:173], v[210:213], v[64:67]
	v_mfma_f32_16x16x32_bf16 v[112:115], v[166:169], v[186:189], v[112:115]
	v_mfma_f32_16x16x32_bf16 v[104:107], v[178:181], v[186:189], v[104:107]
	v_mfma_f32_16x16x32_bf16 v[96:99], v[166:169], v[194:197], v[96:99]
	v_mfma_f32_16x16x32_bf16 v[88:91], v[178:181], v[194:197], v[88:91]
	v_mfma_f32_16x16x32_bf16 v[80:83], v[166:169], v[206:209], v[80:83]
	v_mfma_f32_16x16x32_bf16 v[72:75], v[178:181], v[206:209], v[72:75]
	v_mfma_f32_16x16x32_bf16 v[68:71], v[166:169], v[214:217], v[68:71]
	s_setprio 0
	v_mfma_f32_16x16x32_bf16 v[64:67], v[178:181], v[214:217], v[64:67]
	s_barrier
	ds_read_b128 v[182:185], v145 offset:16384
	ds_read_b128 v[186:189], v145 offset:17408
	ds_read_b128 v[190:193], v145 offset:18432
	ds_read_b128 v[194:197], v145 offset:19456
	ds_read_b128 v[198:201], v145 offset:20480
	ds_read_b128 v[206:209], v145 offset:21504
	ds_read_b128 v[210:213], v145 offset:22528
	ds_read_b128 v[214:217], v145 offset:23552
	s_add_i32 s0, s58, s48
	s_mov_b32 m0, s0
	v_lshl_add_u64 v[174:175], s[30:31], 0, v[132:133]
	global_load_lds_dwordx4 v[174:175], off
	s_add_i32 m0, s0, 0x2000
	s_add_u32 s0, s30, 0x80000
	v_lshl_add_u64 v[202:203], s[30:31], 0, v[128:129]
	s_addc_u32 s1, s31, 0
	s_add_i32 s2, s59, s48
	global_load_lds_dwordx4 v[202:203], off
	v_lshl_add_u64 v[218:219], s[0:1], 0, v[132:133]
	s_mov_b32 m0, s2
	v_lshl_add_u64 v[220:221], s[34:35], 0, v[130:131]
	global_load_lds_dwordx4 v[218:219], off
	s_add_i32 m0, s2, 0x2000
	v_lshl_add_u64 v[218:219], s[0:1], 0, v[128:129]
	global_load_lds_dwordx4 v[218:219], off
	s_mov_b32 m0, s27
	v_lshl_add_u64 v[218:219], s[34:35], 0, v[134:135]
	global_load_lds_dwordx4 v[218:219], off
	s_mov_b32 m0, s50
	s_nop 0
	global_load_lds_dwordx4 v[220:221], off
	s_waitcnt vmcnt(8) lgkmcnt(0)
	s_setprio 1
	s_barrier
	v_mfma_f32_16x16x32_bf16 v[60:63], v[146:149], v[182:185], v[60:63]
	v_mfma_f32_16x16x32_bf16 v[56:59], v[154:157], v[182:185], v[56:59]
	v_mfma_f32_16x16x32_bf16 v[52:55], v[146:149], v[190:193], v[52:55]
	v_mfma_f32_16x16x32_bf16 v[44:47], v[154:157], v[190:193], v[44:47]
	v_mfma_f32_16x16x32_bf16 v[36:39], v[146:149], v[198:201], v[36:39]
	v_mfma_f32_16x16x32_bf16 v[28:31], v[154:157], v[198:201], v[28:31]
	v_mfma_f32_16x16x32_bf16 v[20:23], v[146:149], v[210:213], v[20:23]
	v_mfma_f32_16x16x32_bf16 v[12:15], v[154:157], v[210:213], v[12:15]
	v_mfma_f32_16x16x32_bf16 v[60:63], v[150:153], v[186:189], v[60:63]
	v_mfma_f32_16x16x32_bf16 v[56:59], v[158:161], v[186:189], v[56:59]
	v_mfma_f32_16x16x32_bf16 v[52:55], v[150:153], v[194:197], v[52:55]
	v_mfma_f32_16x16x32_bf16 v[44:47], v[158:161], v[194:197], v[44:47]
	v_mfma_f32_16x16x32_bf16 v[36:39], v[150:153], v[206:209], v[36:39]
	v_mfma_f32_16x16x32_bf16 v[28:31], v[158:161], v[206:209], v[28:31]
	v_mfma_f32_16x16x32_bf16 v[20:23], v[150:153], v[214:217], v[20:23]
	v_mfma_f32_16x16x32_bf16 v[12:15], v[158:161], v[214:217], v[12:15]
	v_mfma_f32_16x16x32_bf16 v[48:51], v[162:165], v[182:185], v[48:51]
	v_mfma_f32_16x16x32_bf16 v[40:43], v[170:173], v[182:185], v[40:43]
	v_mfma_f32_16x16x32_bf16 v[32:35], v[162:165], v[190:193], v[32:35]
	v_mfma_f32_16x16x32_bf16 v[24:27], v[170:173], v[190:193], v[24:27]
	v_mfma_f32_16x16x32_bf16 v[16:19], v[162:165], v[198:201], v[16:19]
	v_mfma_f32_16x16x32_bf16 v[8:11], v[170:173], v[198:201], v[8:11]
	v_mfma_f32_16x16x32_bf16 v[4:7], v[162:165], v[210:213], v[4:7]
	v_mfma_f32_16x16x32_bf16 v[0:3], v[170:173], v[210:213], v[0:3]
	v_mfma_f32_16x16x32_bf16 v[48:51], v[166:169], v[186:189], v[48:51]
	v_mfma_f32_16x16x32_bf16 v[40:43], v[178:181], v[186:189], v[40:43]
	v_mfma_f32_16x16x32_bf16 v[32:35], v[166:169], v[194:197], v[32:35]
	v_mfma_f32_16x16x32_bf16 v[24:27], v[178:181], v[194:197], v[24:27]
	v_mfma_f32_16x16x32_bf16 v[16:19], v[166:169], v[206:209], v[16:19]
	v_mfma_f32_16x16x32_bf16 v[8:11], v[178:181], v[206:209], v[8:11]
	v_mfma_f32_16x16x32_bf16 v[4:7], v[166:169], v[214:217], v[4:7]
	s_setprio 0
	v_mfma_f32_16x16x32_bf16 v[0:3], v[178:181], v[214:217], v[0:3]
	s_barrier
	ds_read_b128 v[182:185], v145 offset:32768
	ds_read_b128 v[186:189], v145 offset:33792
	ds_read_b128 v[190:193], v145 offset:34816
	ds_read_b128 v[194:197], v145 offset:35840
	ds_read_b128 v[198:201], v145 offset:36864
	ds_read_b128 v[206:209], v145 offset:37888
	ds_read_b128 v[210:213], v145 offset:38912
	ds_read_b128 v[214:217], v145 offset:39936
	s_add_i32 s2, 0, 0x18000
	s_add_i32 s38, 0, 0x1c000
	v_add_u32_e32 v158, s2, v142
	v_add_u32_e32 v177, s38, v142
	ds_read_b128 v[146:149], v158
	ds_read_b128 v[150:153], v158 offset:1024
	ds_read_b128 v[154:157], v158 offset:2048
	ds_read_b128 v[158:161], v158 offset:3072
	ds_read_b128 v[162:165], v177
	ds_read_b128 v[166:169], v177 offset:1024
	ds_read_b128 v[170:173], v177 offset:2048
	ds_read_b128 v[178:181], v177 offset:3072
	s_add_u32 s0, s34, 0x80000
	s_addc_u32 s1, s35, 0
	s_mov_b32 m0, s51
	v_lshl_add_u64 v[222:223], s[0:1], 0, v[134:135]
	global_load_lds_dwordx4 v[222:223], off
	s_mov_b32 m0, s52
	v_lshl_add_u64 v[222:223], s[0:1], 0, v[130:131]
	global_load_lds_dwordx4 v[222:223], off
	s_waitcnt vmcnt(8) lgkmcnt(0)
	s_setprio 1
	s_barrier
	v_mfma_f32_16x16x32_bf16 v[124:127], v[146:149], v[182:185], v[124:127]
	v_mfma_f32_16x16x32_bf16 v[120:123], v[154:157], v[182:185], v[120:123]
	v_mfma_f32_16x16x32_bf16 v[116:119], v[146:149], v[190:193], v[116:119]
	v_mfma_f32_16x16x32_bf16 v[108:111], v[154:157], v[190:193], v[108:111]
	v_mfma_f32_16x16x32_bf16 v[100:103], v[146:149], v[198:201], v[100:103]
	v_mfma_f32_16x16x32_bf16 v[92:95], v[154:157], v[198:201], v[92:95]
	v_mfma_f32_16x16x32_bf16 v[84:87], v[146:149], v[210:213], v[84:87]
	v_mfma_f32_16x16x32_bf16 v[76:79], v[154:157], v[210:213], v[76:79]
	v_mfma_f32_16x16x32_bf16 v[124:127], v[150:153], v[186:189], v[124:127]
	v_mfma_f32_16x16x32_bf16 v[120:123], v[158:161], v[186:189], v[120:123]
	v_mfma_f32_16x16x32_bf16 v[116:119], v[150:153], v[194:197], v[116:119]
	v_mfma_f32_16x16x32_bf16 v[108:111], v[158:161], v[194:197], v[108:111]
	v_mfma_f32_16x16x32_bf16 v[100:103], v[150:153], v[206:209], v[100:103]
	v_mfma_f32_16x16x32_bf16 v[92:95], v[158:161], v[206:209], v[92:95]
	v_mfma_f32_16x16x32_bf16 v[84:87], v[150:153], v[214:217], v[84:87]
	v_mfma_f32_16x16x32_bf16 v[76:79], v[158:161], v[214:217], v[76:79]
	v_mfma_f32_16x16x32_bf16 v[112:115], v[162:165], v[182:185], v[112:115]
	v_mfma_f32_16x16x32_bf16 v[104:107], v[170:173], v[182:185], v[104:107]
	v_mfma_f32_16x16x32_bf16 v[96:99], v[162:165], v[190:193], v[96:99]
	v_mfma_f32_16x16x32_bf16 v[88:91], v[170:173], v[190:193], v[88:91]
	v_mfma_f32_16x16x32_bf16 v[80:83], v[162:165], v[198:201], v[80:83]
	v_mfma_f32_16x16x32_bf16 v[72:75], v[170:173], v[198:201], v[72:75]
	v_mfma_f32_16x16x32_bf16 v[68:71], v[162:165], v[210:213], v[68:71]
	v_mfma_f32_16x16x32_bf16 v[64:67], v[170:173], v[210:213], v[64:67]
	v_mfma_f32_16x16x32_bf16 v[112:115], v[166:169], v[186:189], v[112:115]
	v_mfma_f32_16x16x32_bf16 v[104:107], v[178:181], v[186:189], v[104:107]
	v_mfma_f32_16x16x32_bf16 v[96:99], v[166:169], v[194:197], v[96:99]
	v_mfma_f32_16x16x32_bf16 v[88:91], v[178:181], v[194:197], v[88:91]
	v_mfma_f32_16x16x32_bf16 v[80:83], v[166:169], v[206:209], v[80:83]
	v_mfma_f32_16x16x32_bf16 v[72:75], v[178:181], v[206:209], v[72:75]
	v_mfma_f32_16x16x32_bf16 v[68:71], v[166:169], v[214:217], v[68:71]
	s_setprio 0
	v_mfma_f32_16x16x32_bf16 v[64:67], v[178:181], v[214:217], v[64:67]
	s_barrier
	ds_read_b128 v[182:185], v145 offset:49152
	ds_read_b128 v[186:189], v145 offset:50176
	ds_read_b128 v[190:193], v145 offset:51200
	ds_read_b128 v[194:197], v145 offset:52224
	ds_read_b128 v[198:201], v145 offset:53248
	ds_read_b128 v[206:209], v145 offset:54272
	ds_read_b128 v[210:213], v145 offset:55296
	ds_read_b128 v[214:217], v145 offset:56320
	s_add_i32 s0, s2, s48
	s_mov_b32 m0, s0
	v_lshl_add_u64 v[174:175], v[174:175], 0, s[8:9]
	global_load_lds_dwordx4 v[174:175], off
	s_add_i32 m0, s0, 0x2000
	s_add_u32 s0, s30, 0x80080
	v_lshl_add_u64 v[174:175], v[202:203], 0, s[8:9]
	s_addc_u32 s1, s31, 0
	s_add_i32 s2, s38, s48
	global_load_lds_dwordx4 v[174:175], off
	s_mov_b32 m0, s2
	v_lshl_add_u64 v[174:175], s[0:1], 0, v[132:133]
	global_load_lds_dwordx4 v[174:175], off
	s_add_i32 m0, s2, 0x2000
	v_lshl_add_u64 v[174:175], s[0:1], 0, v[128:129]
	global_load_lds_dwordx4 v[174:175], off
	s_mov_b32 m0, s55
	v_lshl_add_u64 v[174:175], v[218:219], 0, s[8:9]
	global_load_lds_dwordx4 v[174:175], off
	s_mov_b32 m0, s56
	v_lshl_add_u64 v[174:175], v[220:221], 0, s[8:9]
	global_load_lds_dwordx4 v[174:175], off
	s_waitcnt vmcnt(8) lgkmcnt(0)
	s_setprio 1
	s_barrier
	v_mfma_f32_16x16x32_bf16 v[60:63], v[146:149], v[182:185], v[60:63]
	v_mfma_f32_16x16x32_bf16 v[56:59], v[154:157], v[182:185], v[56:59]
	v_mfma_f32_16x16x32_bf16 v[52:55], v[146:149], v[190:193], v[52:55]
	v_mfma_f32_16x16x32_bf16 v[44:47], v[154:157], v[190:193], v[44:47]
	v_mfma_f32_16x16x32_bf16 v[36:39], v[146:149], v[198:201], v[36:39]
	v_mfma_f32_16x16x32_bf16 v[28:31], v[154:157], v[198:201], v[28:31]
	v_mfma_f32_16x16x32_bf16 v[20:23], v[146:149], v[210:213], v[20:23]
	v_mfma_f32_16x16x32_bf16 v[12:15], v[154:157], v[210:213], v[12:15]
	v_mfma_f32_16x16x32_bf16 v[60:63], v[150:153], v[186:189], v[60:63]
	v_mfma_f32_16x16x32_bf16 v[56:59], v[158:161], v[186:189], v[56:59]
	v_mfma_f32_16x16x32_bf16 v[52:55], v[150:153], v[194:197], v[52:55]
	v_mfma_f32_16x16x32_bf16 v[44:47], v[158:161], v[194:197], v[44:47]
	v_mfma_f32_16x16x32_bf16 v[36:39], v[150:153], v[206:209], v[36:39]
	v_mfma_f32_16x16x32_bf16 v[28:31], v[158:161], v[206:209], v[28:31]
	v_mfma_f32_16x16x32_bf16 v[20:23], v[150:153], v[214:217], v[20:23]
	v_mfma_f32_16x16x32_bf16 v[12:15], v[158:161], v[214:217], v[12:15]
	v_mfma_f32_16x16x32_bf16 v[48:51], v[162:165], v[182:185], v[48:51]
	v_mfma_f32_16x16x32_bf16 v[40:43], v[170:173], v[182:185], v[40:43]
	v_mfma_f32_16x16x32_bf16 v[32:35], v[162:165], v[190:193], v[32:35]
	v_mfma_f32_16x16x32_bf16 v[24:27], v[170:173], v[190:193], v[24:27]
	v_mfma_f32_16x16x32_bf16 v[16:19], v[162:165], v[198:201], v[16:19]
	v_mfma_f32_16x16x32_bf16 v[8:11], v[170:173], v[198:201], v[8:11]
	v_mfma_f32_16x16x32_bf16 v[4:7], v[162:165], v[210:213], v[4:7]
	v_mfma_f32_16x16x32_bf16 v[0:3], v[170:173], v[210:213], v[0:3]
	v_mfma_f32_16x16x32_bf16 v[48:51], v[166:169], v[186:189], v[48:51]
	s_add_i32 s68, s68, 2
	v_mfma_f32_16x16x32_bf16 v[40:43], v[178:181], v[186:189], v[40:43]
	s_add_u32 s28, s28, 0x100
	v_mfma_f32_16x16x32_bf16 v[32:35], v[166:169], v[194:197], v[32:35]
	s_addc_u32 s29, s29, 0
	v_mfma_f32_16x16x32_bf16 v[24:27], v[178:181], v[194:197], v[24:27]
	s_add_u32 s66, s66, 0x100
	v_mfma_f32_16x16x32_bf16 v[16:19], v[166:169], v[206:209], v[16:19]
	s_addc_u32 s67, s67, 0
	v_mfma_f32_16x16x32_bf16 v[8:11], v[178:181], v[206:209], v[8:11]
	s_cmp_gt_u32 s68, 29
	v_mfma_f32_16x16x32_bf16 v[4:7], v[166:169], v[214:217], v[4:7]
	s_setprio 0
	v_mfma_f32_16x16x32_bf16 v[0:3], v[178:181], v[214:217], v[0:3]
	s_barrier
	s_cbranch_scc0 .LBB0_92
	s_and_b64 vcc, exec, s[10:11]
	s_cbranch_vccz .LBB0_95
	s_barrier

.LBB0_300:
	ds_read_b128 v[128:131], v157
	ds_read_b128 v[132:135], v157 offset:1024
	ds_read_b128 v[136:139], v157 offset:2048
	ds_read_b128 v[140:143], v157 offset:3072
	ds_read_b128 v[160:163], v158
	ds_read_b128 v[164:167], v158 offset:1024
	ds_read_b128 v[168:171], v158 offset:2048
	ds_read_b128 v[172:175], v158 offset:3072
	ds_read_b128 v[178:181], v159
	ds_read_b128 v[182:185], v159 offset:1024
	ds_read_b128 v[186:189], v159 offset:2048
	ds_read_b128 v[190:193], v159 offset:3072
	ds_read_b128 v[194:197], v159 offset:4096
	ds_read_b128 v[198:201], v159 offset:5120
	ds_read_b128 v[206:209], v159 offset:6144
	ds_read_b128 v[210:213], v159 offset:7168
	s_add_i32 m0, s72, 0xc000
	v_lshl_add_u64 v[152:153], s[62:63], 0, v[148:149]
	global_load_lds_dwordx4 v[152:153], off
	s_add_i32 m0, s72, 0xe000
	v_lshl_add_u64 v[152:153], s[62:63], 0, v[150:151]
	global_load_lds_dwordx4 v[152:153], off
	s_waitcnt vmcnt(8) lgkmcnt(0)
	s_setprio 1
	s_barrier
	v_mfma_f32_16x16x32_bf16 v[124:127], v[128:131], v[178:181], v[124:127]
	v_mfma_f32_16x16x32_bf16 v[120:123], v[136:139], v[178:181], v[120:123]
	v_mfma_f32_16x16x32_bf16 v[112:115], v[128:131], v[186:189], v[112:115]
	s_add_u32 s0, s62, 0xfff80080
	v_mfma_f32_16x16x32_bf16 v[108:111], v[136:139], v[186:189], v[108:111]
	s_addc_u32 s1, s63, -1
	v_mfma_f32_16x16x32_bf16 v[96:99], v[128:131], v[194:197], v[96:99]
	s_cmp_eq_u32 s89, 28
	v_mfma_f32_16x16x32_bf16 v[92:95], v[136:139], v[194:197], v[92:95]
	s_cselect_b32 s67, s14, s1
	v_mfma_f32_16x16x32_bf16 v[80:83], v[128:131], v[206:209], v[80:83]
	s_cselect_b32 s66, s49, s0
	v_mfma_f32_16x16x32_bf16 v[76:79], v[136:139], v[206:209], v[76:79]
	s_cselect_b32 s65, s61, s88
	v_mfma_f32_16x16x32_bf16 v[124:127], v[132:135], v[182:185], v[124:127]
	s_cselect_b32 s64, s68, s69
	v_mfma_f32_16x16x32_bf16 v[120:123], v[140:143], v[182:185], v[120:123]
	v_mfma_f32_16x16x32_bf16 v[112:115], v[132:135], v[190:193], v[112:115]
	v_mfma_f32_16x16x32_bf16 v[108:111], v[140:143], v[190:193], v[108:111]
	v_mfma_f32_16x16x32_bf16 v[96:99], v[132:135], v[198:201], v[96:99]
	v_mfma_f32_16x16x32_bf16 v[92:95], v[140:143], v[198:201], v[92:95]
	v_mfma_f32_16x16x32_bf16 v[80:83], v[132:135], v[210:213], v[80:83]
	v_mfma_f32_16x16x32_bf16 v[76:79], v[140:143], v[210:213], v[76:79]
	v_mfma_f32_16x16x32_bf16 v[116:119], v[160:163], v[178:181], v[116:119]
	v_mfma_f32_16x16x32_bf16 v[104:107], v[168:171], v[178:181], v[104:107]
	v_mfma_f32_16x16x32_bf16 v[100:103], v[160:163], v[186:189], v[100:103]
	v_mfma_f32_16x16x32_bf16 v[88:91], v[168:171], v[186:189], v[88:91]
	v_mfma_f32_16x16x32_bf16 v[84:87], v[160:163], v[194:197], v[84:87]
	v_mfma_f32_16x16x32_bf16 v[72:75], v[168:171], v[194:197], v[72:75]
	v_mfma_f32_16x16x32_bf16 v[68:71], v[160:163], v[206:209], v[68:71]
	v_mfma_f32_16x16x32_bf16 v[64:67], v[168:171], v[206:209], v[64:67]
	v_mfma_f32_16x16x32_bf16 v[116:119], v[164:167], v[182:185], v[116:119]
	v_mfma_f32_16x16x32_bf16 v[104:107], v[172:175], v[182:185], v[104:107]
	v_mfma_f32_16x16x32_bf16 v[100:103], v[164:167], v[190:193], v[100:103]
	v_mfma_f32_16x16x32_bf16 v[88:91], v[172:175], v[190:193], v[88:91]
	v_mfma_f32_16x16x32_bf16 v[84:87], v[164:167], v[198:201], v[84:87]
	v_mfma_f32_16x16x32_bf16 v[72:75], v[172:175], v[198:201], v[72:75]
	v_mfma_f32_16x16x32_bf16 v[68:71], v[164:167], v[210:213], v[68:71]
	s_setprio 0
	v_mfma_f32_16x16x32_bf16 v[64:67], v[172:175], v[210:213], v[64:67]
	s_barrier
	ds_read_b128 v[178:181], v159 offset:16384
	ds_read_b128 v[182:185], v159 offset:17408
	ds_read_b128 v[186:189], v159 offset:18432
	ds_read_b128 v[190:193], v159 offset:19456
	ds_read_b128 v[194:197], v159 offset:20480
	ds_read_b128 v[198:201], v159 offset:21504
	ds_read_b128 v[206:209], v159 offset:22528
	ds_read_b128 v[210:213], v159 offset:23552
	s_add_i32 s0, s83, s71
	s_mov_b32 m0, s0
	v_lshl_add_u64 v[152:153], s[64:65], 0, v[146:147]
	global_load_lds_dwordx4 v[152:153], off
	s_add_i32 m0, s0, 0x2000
	s_add_u32 s0, s64, 0x80000
	v_lshl_add_u64 v[202:203], s[64:65], 0, v[144:145]
	s_addc_u32 s1, s65, 0
	s_add_i32 s2, s84, s71
	global_load_lds_dwordx4 v[202:203], off
	v_lshl_add_u64 v[214:215], s[0:1], 0, v[146:147]
	s_mov_b32 m0, s2
	v_lshl_add_u64 v[216:217], s[66:67], 0, v[144:145]
	global_load_lds_dwordx4 v[214:215], off
	s_add_i32 m0, s2, 0x2000
	v_lshl_add_u64 v[214:215], s[0:1], 0, v[144:145]
	global_load_lds_dwordx4 v[214:215], off
	s_mov_b32 m0, s72
	v_lshl_add_u64 v[214:215], s[66:67], 0, v[146:147]
	global_load_lds_dwordx4 v[214:215], off
	s_mov_b32 m0, s73
	s_nop 0
	global_load_lds_dwordx4 v[216:217], off
	s_waitcnt vmcnt(8) lgkmcnt(0)
	s_setprio 1
	s_barrier
	v_mfma_f32_16x16x32_bf16 v[60:63], v[128:131], v[178:181], v[60:63]
	v_mfma_f32_16x16x32_bf16 v[56:59], v[136:139], v[178:181], v[56:59]
	v_mfma_f32_16x16x32_bf16 v[48:51], v[128:131], v[186:189], v[48:51]
	v_mfma_f32_16x16x32_bf16 v[44:47], v[136:139], v[186:189], v[44:47]
	v_mfma_f32_16x16x32_bf16 v[32:35], v[128:131], v[194:197], v[32:35]
	v_mfma_f32_16x16x32_bf16 v[28:31], v[136:139], v[194:197], v[28:31]
	v_mfma_f32_16x16x32_bf16 v[16:19], v[128:131], v[206:209], v[16:19]
	v_mfma_f32_16x16x32_bf16 v[12:15], v[136:139], v[206:209], v[12:15]
	v_mfma_f32_16x16x32_bf16 v[60:63], v[132:135], v[182:185], v[60:63]
	v_mfma_f32_16x16x32_bf16 v[56:59], v[140:143], v[182:185], v[56:59]
	v_mfma_f32_16x16x32_bf16 v[48:51], v[132:135], v[190:193], v[48:51]
	v_mfma_f32_16x16x32_bf16 v[44:47], v[140:143], v[190:193], v[44:47]
	v_mfma_f32_16x16x32_bf16 v[32:35], v[132:135], v[198:201], v[32:35]
	v_mfma_f32_16x16x32_bf16 v[28:31], v[140:143], v[198:201], v[28:31]
	v_mfma_f32_16x16x32_bf16 v[16:19], v[132:135], v[210:213], v[16:19]
	v_mfma_f32_16x16x32_bf16 v[12:15], v[140:143], v[210:213], v[12:15]
	v_mfma_f32_16x16x32_bf16 v[52:55], v[160:163], v[178:181], v[52:55]
	v_mfma_f32_16x16x32_bf16 v[40:43], v[168:171], v[178:181], v[40:43]
	v_mfma_f32_16x16x32_bf16 v[36:39], v[160:163], v[186:189], v[36:39]
	v_mfma_f32_16x16x32_bf16 v[24:27], v[168:171], v[186:189], v[24:27]
	v_mfma_f32_16x16x32_bf16 v[20:23], v[160:163], v[194:197], v[20:23]
	v_mfma_f32_16x16x32_bf16 v[8:11], v[168:171], v[194:197], v[8:11]
	v_mfma_f32_16x16x32_bf16 v[4:7], v[160:163], v[206:209], v[4:7]
	v_mfma_f32_16x16x32_bf16 v[0:3], v[168:171], v[206:209], v[0:3]
	v_mfma_f32_16x16x32_bf16 v[52:55], v[164:167], v[182:185], v[52:55]
	v_mfma_f32_16x16x32_bf16 v[40:43], v[172:175], v[182:185], v[40:43]
	v_mfma_f32_16x16x32_bf16 v[36:39], v[164:167], v[190:193], v[36:39]
	v_mfma_f32_16x16x32_bf16 v[24:27], v[172:175], v[190:193], v[24:27]
	v_mfma_f32_16x16x32_bf16 v[20:23], v[164:167], v[198:201], v[20:23]
	v_mfma_f32_16x16x32_bf16 v[8:11], v[172:175], v[198:201], v[8:11]
	v_mfma_f32_16x16x32_bf16 v[4:7], v[164:167], v[210:213], v[4:7]
	s_setprio 0
	v_mfma_f32_16x16x32_bf16 v[0:3], v[172:175], v[210:213], v[0:3]
	s_barrier
	ds_read_b128 v[178:181], v159 offset:32768
	ds_read_b128 v[182:185], v159 offset:33792
	ds_read_b128 v[186:189], v159 offset:34816
	ds_read_b128 v[190:193], v159 offset:35840
	ds_read_b128 v[194:197], v159 offset:36864
	ds_read_b128 v[198:201], v159 offset:37888
	ds_read_b128 v[206:209], v159 offset:38912
	ds_read_b128 v[210:213], v159 offset:39936
	s_add_i32 s2, 0, 0x18000
	s_add_i32 s3, 0, 0x1c000
	v_add_u32_e32 v140, s2, v156
	v_add_u32_e32 v172, s3, v156
	ds_read_b128 v[128:131], v140
	ds_read_b128 v[132:135], v140 offset:1024
	ds_read_b128 v[136:139], v140 offset:2048
	ds_read_b128 v[140:143], v140 offset:3072
	ds_read_b128 v[160:163], v172
	ds_read_b128 v[164:167], v172 offset:1024
	ds_read_b128 v[168:171], v172 offset:2048
	ds_read_b128 v[172:175], v172 offset:3072
	s_add_u32 s0, s66, 0x80000
	s_addc_u32 s1, s67, 0
	s_mov_b32 m0, s74
	v_lshl_add_u64 v[218:219], s[0:1], 0, v[146:147]
	global_load_lds_dwordx4 v[218:219], off
	s_mov_b32 m0, s75
	v_lshl_add_u64 v[218:219], s[0:1], 0, v[144:145]
	global_load_lds_dwordx4 v[218:219], off
	s_waitcnt vmcnt(8) lgkmcnt(0)
	s_setprio 1
	s_barrier
	v_mfma_f32_16x16x32_bf16 v[124:127], v[128:131], v[178:181], v[124:127]
	v_mfma_f32_16x16x32_bf16 v[120:123], v[136:139], v[178:181], v[120:123]
	v_mfma_f32_16x16x32_bf16 v[112:115], v[128:131], v[186:189], v[112:115]
	v_mfma_f32_16x16x32_bf16 v[108:111], v[136:139], v[186:189], v[108:111]
	v_mfma_f32_16x16x32_bf16 v[96:99], v[128:131], v[194:197], v[96:99]
	v_mfma_f32_16x16x32_bf16 v[92:95], v[136:139], v[194:197], v[92:95]
	v_mfma_f32_16x16x32_bf16 v[80:83], v[128:131], v[206:209], v[80:83]
	v_mfma_f32_16x16x32_bf16 v[76:79], v[136:139], v[206:209], v[76:79]
	v_mfma_f32_16x16x32_bf16 v[124:127], v[132:135], v[182:185], v[124:127]
	v_mfma_f32_16x16x32_bf16 v[120:123], v[140:143], v[182:185], v[120:123]
	v_mfma_f32_16x16x32_bf16 v[112:115], v[132:135], v[190:193], v[112:115]
	v_mfma_f32_16x16x32_bf16 v[108:111], v[140:143], v[190:193], v[108:111]
	v_mfma_f32_16x16x32_bf16 v[96:99], v[132:135], v[198:201], v[96:99]
	v_mfma_f32_16x16x32_bf16 v[92:95], v[140:143], v[198:201], v[92:95]
	v_mfma_f32_16x16x32_bf16 v[80:83], v[132:135], v[210:213], v[80:83]
	v_mfma_f32_16x16x32_bf16 v[76:79], v[140:143], v[210:213], v[76:79]
	v_mfma_f32_16x16x32_bf16 v[116:119], v[160:163], v[178:181], v[116:119]
	v_mfma_f32_16x16x32_bf16 v[104:107], v[168:171], v[178:181], v[104:107]
	v_mfma_f32_16x16x32_bf16 v[100:103], v[160:163], v[186:189], v[100:103]
	v_mfma_f32_16x16x32_bf16 v[88:91], v[168:171], v[186:189], v[88:91]
	v_mfma_f32_16x16x32_bf16 v[84:87], v[160:163], v[194:197], v[84:87]
	v_mfma_f32_16x16x32_bf16 v[72:75], v[168:171], v[194:197], v[72:75]
	v_mfma_f32_16x16x32_bf16 v[68:71], v[160:163], v[206:209], v[68:71]
	v_mfma_f32_16x16x32_bf16 v[64:67], v[168:171], v[206:209], v[64:67]
	v_mfma_f32_16x16x32_bf16 v[116:119], v[164:167], v[182:185], v[116:119]
	v_mfma_f32_16x16x32_bf16 v[104:107], v[172:175], v[182:185], v[104:107]
	v_mfma_f32_16x16x32_bf16 v[100:103], v[164:167], v[190:193], v[100:103]
	v_mfma_f32_16x16x32_bf16 v[88:91], v[172:175], v[190:193], v[88:91]
	v_mfma_f32_16x16x32_bf16 v[84:87], v[164:167], v[198:201], v[84:87]
	v_mfma_f32_16x16x32_bf16 v[72:75], v[172:175], v[198:201], v[72:75]
	v_mfma_f32_16x16x32_bf16 v[68:71], v[164:167], v[210:213], v[68:71]
	s_setprio 0
	v_mfma_f32_16x16x32_bf16 v[64:67], v[172:175], v[210:213], v[64:67]
	s_barrier
	ds_read_b128 v[178:181], v159 offset:49152
	ds_read_b128 v[182:185], v159 offset:50176
	ds_read_b128 v[186:189], v159 offset:51200
	ds_read_b128 v[190:193], v159 offset:52224
	ds_read_b128 v[194:197], v159 offset:53248
	ds_read_b128 v[198:201], v159 offset:54272
	ds_read_b128 v[206:209], v159 offset:55296
	ds_read_b128 v[210:213], v159 offset:56320
	s_add_i32 s0, s2, s71
	s_mov_b32 m0, s0
	v_lshl_add_u64 v[152:153], v[152:153], 0, s[12:13]
	global_load_lds_dwordx4 v[152:153], off
	s_add_i32 m0, s0, 0x2000
	s_add_u32 s0, s64, 0x80080
	v_lshl_add_u64 v[152:153], v[202:203], 0, s[12:13]
	s_addc_u32 s1, s65, 0
	s_add_i32 s2, s3, s71
	global_load_lds_dwordx4 v[152:153], off
	s_mov_b32 m0, s2
	v_lshl_add_u64 v[152:153], s[0:1], 0, v[146:147]
	global_load_lds_dwordx4 v[152:153], off
	s_add_i32 m0, s2, 0x2000
	v_lshl_add_u64 v[152:153], s[0:1], 0, v[144:145]
	global_load_lds_dwordx4 v[152:153], off
	s_mov_b32 m0, s81
	v_lshl_add_u64 v[152:153], v[214:215], 0, s[12:13]
	global_load_lds_dwordx4 v[152:153], off
	s_mov_b32 m0, s82
	v_lshl_add_u64 v[152:153], v[216:217], 0, s[12:13]
	global_load_lds_dwordx4 v[152:153], off
	s_waitcnt vmcnt(8) lgkmcnt(0)
	s_setprio 1
	s_barrier
	v_mfma_f32_16x16x32_bf16 v[60:63], v[128:131], v[178:181], v[60:63]
	v_mfma_f32_16x16x32_bf16 v[56:59], v[136:139], v[178:181], v[56:59]
	v_mfma_f32_16x16x32_bf16 v[48:51], v[128:131], v[186:189], v[48:51]
	v_mfma_f32_16x16x32_bf16 v[44:47], v[136:139], v[186:189], v[44:47]
	v_mfma_f32_16x16x32_bf16 v[32:35], v[128:131], v[194:197], v[32:35]
	v_mfma_f32_16x16x32_bf16 v[28:31], v[136:139], v[194:197], v[28:31]
	v_mfma_f32_16x16x32_bf16 v[16:19], v[128:131], v[206:209], v[16:19]
	v_mfma_f32_16x16x32_bf16 v[12:15], v[136:139], v[206:209], v[12:15]
	v_mfma_f32_16x16x32_bf16 v[60:63], v[132:135], v[182:185], v[60:63]
	v_mfma_f32_16x16x32_bf16 v[56:59], v[140:143], v[182:185], v[56:59]
	v_mfma_f32_16x16x32_bf16 v[48:51], v[132:135], v[190:193], v[48:51]
	v_mfma_f32_16x16x32_bf16 v[44:47], v[140:143], v[190:193], v[44:47]
	v_mfma_f32_16x16x32_bf16 v[32:35], v[132:135], v[198:201], v[32:35]
	v_mfma_f32_16x16x32_bf16 v[28:31], v[140:143], v[198:201], v[28:31]
	v_mfma_f32_16x16x32_bf16 v[16:19], v[132:135], v[210:213], v[16:19]
	v_mfma_f32_16x16x32_bf16 v[12:15], v[140:143], v[210:213], v[12:15]
	v_mfma_f32_16x16x32_bf16 v[52:55], v[160:163], v[178:181], v[52:55]
	v_mfma_f32_16x16x32_bf16 v[40:43], v[168:171], v[178:181], v[40:43]
	v_mfma_f32_16x16x32_bf16 v[36:39], v[160:163], v[186:189], v[36:39]
	v_mfma_f32_16x16x32_bf16 v[24:27], v[168:171], v[186:189], v[24:27]
	v_mfma_f32_16x16x32_bf16 v[20:23], v[160:163], v[194:197], v[20:23]
	v_mfma_f32_16x16x32_bf16 v[8:11], v[168:171], v[194:197], v[8:11]
	v_mfma_f32_16x16x32_bf16 v[4:7], v[160:163], v[206:209], v[4:7]
	v_mfma_f32_16x16x32_bf16 v[0:3], v[168:171], v[206:209], v[0:3]
	v_mfma_f32_16x16x32_bf16 v[52:55], v[164:167], v[182:185], v[52:55]
	s_add_i32 s89, s89, 2
	v_mfma_f32_16x16x32_bf16 v[40:43], v[172:175], v[182:185], v[40:43]
	s_add_u32 s62, s62, 0x100
	v_mfma_f32_16x16x32_bf16 v[36:39], v[164:167], v[190:193], v[36:39]
	s_addc_u32 s63, s63, 0
	v_mfma_f32_16x16x32_bf16 v[24:27], v[172:175], v[190:193], v[24:27]
	s_add_u32 s69, s69, 0x100
	v_mfma_f32_16x16x32_bf16 v[20:23], v[164:167], v[198:201], v[20:23]
	s_addc_u32 s88, s88, 0
	v_mfma_f32_16x16x32_bf16 v[8:11], v[172:175], v[198:201], v[8:11]
	s_cmp_gt_u32 s89, 29
	v_mfma_f32_16x16x32_bf16 v[4:7], v[164:167], v[210:213], v[4:7]
	s_setprio 0
	v_mfma_f32_16x16x32_bf16 v[0:3], v[172:175], v[210:213], v[0:3]
	s_barrier
	s_cbranch_scc0 .LBB0_300
	s_and_b64 vcc, exec, s[16:17]
	s_cbranch_vccz .LBB0_303
	s_barrier

.LBB0_399:
	ds_read_b128 v[128:131], v207
	ds_read_b128 v[132:135], v207 offset:1024
	ds_read_b128 v[136:139], v207 offset:2048
	ds_read_b128 v[140:143], v207 offset:3072
	ds_read_b128 v[144:147], v208
	ds_read_b128 v[148:151], v208 offset:1024
	ds_read_b128 v[152:155], v208 offset:2048
	ds_read_b128 v[156:159], v208 offset:3072
	ds_read_b128 v[160:163], v209
	ds_read_b128 v[164:167], v209 offset:1024
	ds_read_b128 v[168:171], v209 offset:2048
	ds_read_b128 v[172:175], v209 offset:3072
	ds_read_b128 v[190:193], v209 offset:4096
	ds_read_b128 v[194:197], v209 offset:5120
	ds_read_b128 v[198:201], v209 offset:6144
	ds_read_b128 v[210:213], v209 offset:7168
	s_add_i32 m0, s81, 0xc000
	v_lshl_add_u64 v[202:203], s[4:5], 0, v[186:187]
	global_load_lds_dwordx4 v[202:203], off
	s_add_i32 m0, s81, 0xe000
	v_lshl_add_u64 v[202:203], s[4:5], 0, v[188:189]
	global_load_lds_dwordx4 v[202:203], off
	s_waitcnt vmcnt(8) lgkmcnt(0)
	s_setprio 1
	s_barrier
	v_mfma_f32_16x16x32_bf16 v[124:127], v[128:131], v[160:163], v[124:127]
	v_mfma_f32_16x16x32_bf16 v[56:59], v[136:139], v[160:163], v[56:59]
	v_mfma_f32_16x16x32_bf16 v[116:119], v[128:131], v[168:171], v[116:119]
	s_add_u32 s0, s4, 0xfff80080
	v_mfma_f32_16x16x32_bf16 v[52:55], v[136:139], v[168:171], v[52:55]
	s_addc_u32 s1, s5, -1
	v_mfma_f32_16x16x32_bf16 v[108:111], v[128:131], v[190:193], v[108:111]
	s_cmp_eq_u32 vcc_hi, 28
	v_mfma_f32_16x16x32_bf16 v[44:47], v[136:139], v[190:193], v[44:47]
	s_cselect_b32 s11, s7, s1
	v_mfma_f32_16x16x32_bf16 v[104:107], v[128:131], v[198:201], v[104:107]
	s_cselect_b32 s10, s12, s0
	v_mfma_f32_16x16x32_bf16 v[32:35], v[136:139], v[198:201], v[32:35]
	s_cselect_b32 s9, s13, vcc_lo
	v_mfma_f32_16x16x32_bf16 v[124:127], v[132:135], v[164:167], v[124:127]
	s_cselect_b32 s8, s15, s65
	v_mfma_f32_16x16x32_bf16 v[56:59], v[140:143], v[164:167], v[56:59]
	v_mfma_f32_16x16x32_bf16 v[116:119], v[132:135], v[172:175], v[116:119]
	v_mfma_f32_16x16x32_bf16 v[52:55], v[140:143], v[172:175], v[52:55]
	v_mfma_f32_16x16x32_bf16 v[108:111], v[132:135], v[194:197], v[108:111]
	v_mfma_f32_16x16x32_bf16 v[44:47], v[140:143], v[194:197], v[44:47]
	v_mfma_f32_16x16x32_bf16 v[104:107], v[132:135], v[210:213], v[104:107]
	v_mfma_f32_16x16x32_bf16 v[32:35], v[140:143], v[210:213], v[32:35]
	v_mfma_f32_16x16x32_bf16 v[120:123], v[144:147], v[160:163], v[120:123]
	v_mfma_f32_16x16x32_bf16 v[60:63], v[152:155], v[160:163], v[60:63]
	v_mfma_f32_16x16x32_bf16 v[112:115], v[144:147], v[168:171], v[112:115]
	v_mfma_f32_16x16x32_bf16 v[48:51], v[152:155], v[168:171], v[48:51]
	v_mfma_f32_16x16x32_bf16 v[100:103], v[144:147], v[190:193], v[100:103]
	v_mfma_f32_16x16x32_bf16 v[40:43], v[152:155], v[190:193], v[40:43]
	v_mfma_f32_16x16x32_bf16 v[96:99], v[144:147], v[198:201], v[96:99]
	v_mfma_f32_16x16x32_bf16 v[36:39], v[152:155], v[198:201], v[36:39]
	v_mfma_f32_16x16x32_bf16 v[120:123], v[148:151], v[164:167], v[120:123]
	v_mfma_f32_16x16x32_bf16 v[60:63], v[156:159], v[164:167], v[60:63]
	v_mfma_f32_16x16x32_bf16 v[112:115], v[148:151], v[172:175], v[112:115]
	v_mfma_f32_16x16x32_bf16 v[48:51], v[156:159], v[172:175], v[48:51]
	v_mfma_f32_16x16x32_bf16 v[100:103], v[148:151], v[194:197], v[100:103]
	v_mfma_f32_16x16x32_bf16 v[40:43], v[156:159], v[194:197], v[40:43]
	v_mfma_f32_16x16x32_bf16 v[96:99], v[148:151], v[210:213], v[96:99]
	s_setprio 0
	v_mfma_f32_16x16x32_bf16 v[36:39], v[156:159], v[210:213], v[36:39]
	s_barrier
	ds_read_b128 v[160:163], v209 offset:16384
	ds_read_b128 v[164:167], v209 offset:17408
	ds_read_b128 v[168:171], v209 offset:18432
	ds_read_b128 v[172:175], v209 offset:19456
	ds_read_b128 v[190:193], v209 offset:20480
	ds_read_b128 v[194:197], v209 offset:21504
	ds_read_b128 v[198:201], v209 offset:22528
	ds_read_b128 v[210:213], v209 offset:23552
	s_add_i32 s0, s95, s80
	s_mov_b32 m0, s0
	v_lshl_add_u64 v[202:203], s[8:9], 0, v[180:181]
	global_load_lds_dwordx4 v[202:203], off
	s_add_i32 m0, s0, 0x2000
	s_add_u32 s0, s8, 0x80000
	v_lshl_add_u64 v[214:215], s[8:9], 0, v[184:185]
	s_addc_u32 s1, s9, 0
	s_add_i32 s2, s96, s80
	global_load_lds_dwordx4 v[214:215], off
	v_lshl_add_u64 v[216:217], s[0:1], 0, v[180:181]
	s_mov_b32 m0, s2
	v_lshl_add_u64 v[218:219], s[10:11], 0, v[182:183]
	global_load_lds_dwordx4 v[216:217], off
	s_add_i32 m0, s2, 0x2000
	v_lshl_add_u64 v[216:217], s[0:1], 0, v[184:185]
	global_load_lds_dwordx4 v[216:217], off
	s_mov_b32 m0, s81
	v_lshl_add_u64 v[216:217], s[10:11], 0, v[178:179]
	global_load_lds_dwordx4 v[216:217], off
	s_mov_b32 m0, s82
	s_nop 0
	global_load_lds_dwordx4 v[218:219], off
	s_waitcnt vmcnt(8) lgkmcnt(0)
	s_setprio 1
	s_barrier
	v_mfma_f32_16x16x32_bf16 v[92:95], v[128:131], v[160:163], v[92:95]
	v_mfma_f32_16x16x32_bf16 v[24:27], v[136:139], v[160:163], v[24:27]
	v_mfma_f32_16x16x32_bf16 v[84:87], v[128:131], v[168:171], v[84:87]
	v_mfma_f32_16x16x32_bf16 v[20:23], v[136:139], v[168:171], v[20:23]
	v_mfma_f32_16x16x32_bf16 v[76:79], v[128:131], v[190:193], v[76:79]
	v_mfma_f32_16x16x32_bf16 v[12:15], v[136:139], v[190:193], v[12:15]
	v_mfma_f32_16x16x32_bf16 v[72:75], v[128:131], v[198:201], v[72:75]
	v_mfma_f32_16x16x32_bf16 v[0:3], v[136:139], v[198:201], v[0:3]
	v_mfma_f32_16x16x32_bf16 v[92:95], v[132:135], v[164:167], v[92:95]
	v_mfma_f32_16x16x32_bf16 v[24:27], v[140:143], v[164:167], v[24:27]
	v_mfma_f32_16x16x32_bf16 v[84:87], v[132:135], v[172:175], v[84:87]
	v_mfma_f32_16x16x32_bf16 v[20:23], v[140:143], v[172:175], v[20:23]
	v_mfma_f32_16x16x32_bf16 v[76:79], v[132:135], v[194:197], v[76:79]
	v_mfma_f32_16x16x32_bf16 v[12:15], v[140:143], v[194:197], v[12:15]
	v_mfma_f32_16x16x32_bf16 v[72:75], v[132:135], v[210:213], v[72:75]
	v_mfma_f32_16x16x32_bf16 v[0:3], v[140:143], v[210:213], v[0:3]
	v_mfma_f32_16x16x32_bf16 v[88:91], v[144:147], v[160:163], v[88:91]
	v_mfma_f32_16x16x32_bf16 v[28:31], v[152:155], v[160:163], v[28:31]
	v_mfma_f32_16x16x32_bf16 v[80:83], v[144:147], v[168:171], v[80:83]
	v_mfma_f32_16x16x32_bf16 v[16:19], v[152:155], v[168:171], v[16:19]
	v_mfma_f32_16x16x32_bf16 v[68:71], v[144:147], v[190:193], v[68:71]
	v_mfma_f32_16x16x32_bf16 v[8:11], v[152:155], v[190:193], v[8:11]
	v_mfma_f32_16x16x32_bf16 v[64:67], v[144:147], v[198:201], v[64:67]
	v_mfma_f32_16x16x32_bf16 v[4:7], v[152:155], v[198:201], v[4:7]
	v_mfma_f32_16x16x32_bf16 v[88:91], v[148:151], v[164:167], v[88:91]
	v_mfma_f32_16x16x32_bf16 v[28:31], v[156:159], v[164:167], v[28:31]
	v_mfma_f32_16x16x32_bf16 v[80:83], v[148:151], v[172:175], v[80:83]
	v_mfma_f32_16x16x32_bf16 v[16:19], v[156:159], v[172:175], v[16:19]
	v_mfma_f32_16x16x32_bf16 v[68:71], v[148:151], v[194:197], v[68:71]
	v_mfma_f32_16x16x32_bf16 v[8:11], v[156:159], v[194:197], v[8:11]
	v_mfma_f32_16x16x32_bf16 v[64:67], v[148:151], v[210:213], v[64:67]
	s_setprio 0
	v_mfma_f32_16x16x32_bf16 v[4:7], v[156:159], v[210:213], v[4:7]
	s_barrier
	ds_read_b128 v[160:163], v209 offset:32768
	ds_read_b128 v[164:167], v209 offset:33792
	ds_read_b128 v[168:171], v209 offset:34816
	ds_read_b128 v[172:175], v209 offset:35840
	ds_read_b128 v[190:193], v209 offset:36864
	ds_read_b128 v[194:197], v209 offset:37888
	ds_read_b128 v[198:201], v209 offset:38912
	ds_read_b128 v[210:213], v209 offset:39936
	s_add_i32 s2, 0, 0x18000
	s_add_i32 s3, 0, 0x1c000
	v_add_u32_e32 v140, s2, v206
	v_add_u32_e32 v156, s3, v206
	ds_read_b128 v[128:131], v140
	ds_read_b128 v[132:135], v140 offset:1024
	ds_read_b128 v[136:139], v140 offset:2048
	ds_read_b128 v[140:143], v140 offset:3072
	ds_read_b128 v[144:147], v156
	ds_read_b128 v[148:151], v156 offset:1024
	ds_read_b128 v[152:155], v156 offset:2048
	ds_read_b128 v[156:159], v156 offset:3072
	s_add_u32 s0, s10, 0x80000
	s_addc_u32 s1, s11, 0
	s_mov_b32 m0, s83
	v_lshl_add_u64 v[220:221], s[0:1], 0, v[178:179]
	global_load_lds_dwordx4 v[220:221], off
	s_mov_b32 m0, s84
	v_lshl_add_u64 v[220:221], s[0:1], 0, v[182:183]
	global_load_lds_dwordx4 v[220:221], off
	s_waitcnt vmcnt(8) lgkmcnt(0)
	s_setprio 1
	s_barrier
	v_mfma_f32_16x16x32_bf16 v[124:127], v[128:131], v[160:163], v[124:127]
	v_mfma_f32_16x16x32_bf16 v[56:59], v[136:139], v[160:163], v[56:59]
	v_mfma_f32_16x16x32_bf16 v[116:119], v[128:131], v[168:171], v[116:119]
	v_mfma_f32_16x16x32_bf16 v[52:55], v[136:139], v[168:171], v[52:55]
	v_mfma_f32_16x16x32_bf16 v[108:111], v[128:131], v[190:193], v[108:111]
	v_mfma_f32_16x16x32_bf16 v[44:47], v[136:139], v[190:193], v[44:47]
	v_mfma_f32_16x16x32_bf16 v[104:107], v[128:131], v[198:201], v[104:107]
	v_mfma_f32_16x16x32_bf16 v[32:35], v[136:139], v[198:201], v[32:35]
	v_mfma_f32_16x16x32_bf16 v[124:127], v[132:135], v[164:167], v[124:127]
	v_mfma_f32_16x16x32_bf16 v[56:59], v[140:143], v[164:167], v[56:59]
	v_mfma_f32_16x16x32_bf16 v[116:119], v[132:135], v[172:175], v[116:119]
	v_mfma_f32_16x16x32_bf16 v[52:55], v[140:143], v[172:175], v[52:55]
	v_mfma_f32_16x16x32_bf16 v[108:111], v[132:135], v[194:197], v[108:111]
	v_mfma_f32_16x16x32_bf16 v[44:47], v[140:143], v[194:197], v[44:47]
	v_mfma_f32_16x16x32_bf16 v[104:107], v[132:135], v[210:213], v[104:107]
	v_mfma_f32_16x16x32_bf16 v[32:35], v[140:143], v[210:213], v[32:35]
	v_mfma_f32_16x16x32_bf16 v[120:123], v[144:147], v[160:163], v[120:123]
	v_mfma_f32_16x16x32_bf16 v[60:63], v[152:155], v[160:163], v[60:63]
	v_mfma_f32_16x16x32_bf16 v[112:115], v[144:147], v[168:171], v[112:115]
	v_mfma_f32_16x16x32_bf16 v[48:51], v[152:155], v[168:171], v[48:51]
	v_mfma_f32_16x16x32_bf16 v[100:103], v[144:147], v[190:193], v[100:103]
	v_mfma_f32_16x16x32_bf16 v[40:43], v[152:155], v[190:193], v[40:43]
	v_mfma_f32_16x16x32_bf16 v[96:99], v[144:147], v[198:201], v[96:99]
	v_mfma_f32_16x16x32_bf16 v[36:39], v[152:155], v[198:201], v[36:39]
	v_mfma_f32_16x16x32_bf16 v[120:123], v[148:151], v[164:167], v[120:123]
	v_mfma_f32_16x16x32_bf16 v[60:63], v[156:159], v[164:167], v[60:63]
	v_mfma_f32_16x16x32_bf16 v[112:115], v[148:151], v[172:175], v[112:115]
	v_mfma_f32_16x16x32_bf16 v[48:51], v[156:159], v[172:175], v[48:51]
	v_mfma_f32_16x16x32_bf16 v[100:103], v[148:151], v[194:197], v[100:103]
	v_mfma_f32_16x16x32_bf16 v[40:43], v[156:159], v[194:197], v[40:43]
	v_mfma_f32_16x16x32_bf16 v[96:99], v[148:151], v[210:213], v[96:99]
	s_setprio 0
	v_mfma_f32_16x16x32_bf16 v[36:39], v[156:159], v[210:213], v[36:39]
	s_barrier
	ds_read_b128 v[160:163], v209 offset:49152
	ds_read_b128 v[164:167], v209 offset:50176
	ds_read_b128 v[168:171], v209 offset:51200
	ds_read_b128 v[172:175], v209 offset:52224
	ds_read_b128 v[190:193], v209 offset:53248
	ds_read_b128 v[194:197], v209 offset:54272
	ds_read_b128 v[198:201], v209 offset:55296
	ds_read_b128 v[210:213], v209 offset:56320
	s_add_i32 s0, s2, s80
	s_mov_b32 m0, s0
	v_lshl_add_u64 v[202:203], v[202:203], 0, s[24:25]
	global_load_lds_dwordx4 v[202:203], off
	s_add_i32 m0, s0, 0x2000
	s_add_u32 s0, s8, 0x80080
	v_lshl_add_u64 v[202:203], v[214:215], 0, s[24:25]
	s_addc_u32 s1, s9, 0
	s_add_i32 s2, s3, s80
	global_load_lds_dwordx4 v[202:203], off
	s_mov_b32 m0, s2
	v_lshl_add_u64 v[202:203], s[0:1], 0, v[180:181]
	global_load_lds_dwordx4 v[202:203], off
	s_add_i32 m0, s2, 0x2000
	v_lshl_add_u64 v[202:203], s[0:1], 0, v[184:185]
	global_load_lds_dwordx4 v[202:203], off
	s_mov_b32 m0, s90
	v_lshl_add_u64 v[202:203], v[216:217], 0, s[24:25]
	global_load_lds_dwordx4 v[202:203], off
	s_mov_b32 m0, s91
	v_lshl_add_u64 v[202:203], v[218:219], 0, s[24:25]
	global_load_lds_dwordx4 v[202:203], off
	s_waitcnt vmcnt(8) lgkmcnt(0)
	s_setprio 1
	s_barrier
	v_mfma_f32_16x16x32_bf16 v[92:95], v[128:131], v[160:163], v[92:95]
	v_mfma_f32_16x16x32_bf16 v[24:27], v[136:139], v[160:163], v[24:27]
	v_mfma_f32_16x16x32_bf16 v[84:87], v[128:131], v[168:171], v[84:87]
	v_mfma_f32_16x16x32_bf16 v[20:23], v[136:139], v[168:171], v[20:23]
	v_mfma_f32_16x16x32_bf16 v[76:79], v[128:131], v[190:193], v[76:79]
	v_mfma_f32_16x16x32_bf16 v[12:15], v[136:139], v[190:193], v[12:15]
	v_mfma_f32_16x16x32_bf16 v[72:75], v[128:131], v[198:201], v[72:75]
	v_mfma_f32_16x16x32_bf16 v[0:3], v[136:139], v[198:201], v[0:3]
	v_mfma_f32_16x16x32_bf16 v[92:95], v[132:135], v[164:167], v[92:95]
	v_mfma_f32_16x16x32_bf16 v[24:27], v[140:143], v[164:167], v[24:27]
	v_mfma_f32_16x16x32_bf16 v[84:87], v[132:135], v[172:175], v[84:87]
	v_mfma_f32_16x16x32_bf16 v[20:23], v[140:143], v[172:175], v[20:23]
	v_mfma_f32_16x16x32_bf16 v[76:79], v[132:135], v[194:197], v[76:79]
	v_mfma_f32_16x16x32_bf16 v[12:15], v[140:143], v[194:197], v[12:15]
	v_mfma_f32_16x16x32_bf16 v[72:75], v[132:135], v[210:213], v[72:75]
	v_mfma_f32_16x16x32_bf16 v[0:3], v[140:143], v[210:213], v[0:3]
	v_mfma_f32_16x16x32_bf16 v[88:91], v[144:147], v[160:163], v[88:91]
	v_mfma_f32_16x16x32_bf16 v[28:31], v[152:155], v[160:163], v[28:31]
	v_mfma_f32_16x16x32_bf16 v[80:83], v[144:147], v[168:171], v[80:83]
	v_mfma_f32_16x16x32_bf16 v[16:19], v[152:155], v[168:171], v[16:19]
	v_mfma_f32_16x16x32_bf16 v[68:71], v[144:147], v[190:193], v[68:71]
	v_mfma_f32_16x16x32_bf16 v[8:11], v[152:155], v[190:193], v[8:11]
	v_mfma_f32_16x16x32_bf16 v[64:67], v[144:147], v[198:201], v[64:67]
	v_mfma_f32_16x16x32_bf16 v[4:7], v[152:155], v[198:201], v[4:7]
	v_mfma_f32_16x16x32_bf16 v[88:91], v[148:151], v[164:167], v[88:91]
	s_add_i32 vcc_hi, vcc_hi, 2
	v_mfma_f32_16x16x32_bf16 v[28:31], v[156:159], v[164:167], v[28:31]
	s_add_u32 s4, s4, 0x100
	v_mfma_f32_16x16x32_bf16 v[80:83], v[148:151], v[172:175], v[80:83]
	s_addc_u32 s5, s5, 0
	v_mfma_f32_16x16x32_bf16 v[16:19], v[156:159], v[172:175], v[16:19]
	s_add_u32 s65, s65, 0x100
	v_mfma_f32_16x16x32_bf16 v[68:71], v[148:151], v[194:197], v[68:71]
	s_addc_u32 vcc_lo, vcc_lo, 0
	v_mfma_f32_16x16x32_bf16 v[8:11], v[156:159], v[194:197], v[8:11]
	s_cmp_gt_u32 vcc_hi, 29
	v_mfma_f32_16x16x32_bf16 v[64:67], v[148:151], v[210:213], v[64:67]
	s_setprio 0
	v_mfma_f32_16x16x32_bf16 v[4:7], v[156:159], v[210:213], v[4:7]
	s_barrier
	s_cbranch_scc0 .LBB0_399
	s_and_b64 vcc, exec, s[26:27]
	s_cbranch_vccz .LBB0_402
	s_barrier

.LBB0_541:
	ds_read_b128 v[128:131], v157
	ds_read_b128 v[132:135], v157 offset:1024
	ds_read_b128 v[136:139], v157 offset:2048
	ds_read_b128 v[140:143], v157 offset:3072
	ds_read_b128 v[160:163], v158
	ds_read_b128 v[164:167], v158 offset:1024
	ds_read_b128 v[168:171], v158 offset:2048
	ds_read_b128 v[172:175], v158 offset:3072
	ds_read_b128 v[178:181], v159
	ds_read_b128 v[182:185], v159 offset:1024
	ds_read_b128 v[186:189], v159 offset:2048
	ds_read_b128 v[190:193], v159 offset:3072
	ds_read_b128 v[194:197], v159 offset:4096
	ds_read_b128 v[206:209], v159 offset:5120
	ds_read_b128 v[210:213], v159 offset:6144
	ds_read_b128 v[214:217], v159 offset:7168
	s_add_i32 m0, s66, 0xc000
	v_lshl_add_u64 v[152:153], s[56:57], 0, v[148:149]
	global_load_lds_dwordx4 v[152:153], off
	s_add_i32 m0, s66, 0xe000
	v_lshl_add_u64 v[152:153], s[56:57], 0, v[150:151]
	global_load_lds_dwordx4 v[152:153], off
	s_waitcnt vmcnt(8) lgkmcnt(0)
	s_setprio 1
	s_barrier
	v_mfma_f32_16x16x32_bf16 v[124:127], v[128:131], v[178:181], v[124:127]
	v_mfma_f32_16x16x32_bf16 v[120:123], v[136:139], v[178:181], v[120:123]
	v_mfma_f32_16x16x32_bf16 v[112:115], v[128:131], v[186:189], v[112:115]
	s_add_u32 s58, s56, 0x100
	v_mfma_f32_16x16x32_bf16 v[108:111], v[136:139], v[186:189], v[108:111]
	s_addc_u32 s59, s57, 0
	v_mfma_f32_16x16x32_bf16 v[96:99], v[128:131], v[194:197], v[96:99]
	s_cmpk_eq_i32 s89, 0x54
	v_mfma_f32_16x16x32_bf16 v[92:95], v[136:139], v[194:197], v[92:95]
	s_cselect_b32 s63, s12, s59
	v_mfma_f32_16x16x32_bf16 v[80:83], v[128:131], v[210:213], v[80:83]
	s_cselect_b32 s62, s55, s58
	v_mfma_f32_16x16x32_bf16 v[76:79], v[136:139], v[210:213], v[76:79]
	s_cselect_b32 s61, s85, s88
	v_mfma_f32_16x16x32_bf16 v[124:127], v[132:135], v[182:185], v[124:127]
	s_cselect_b32 s60, s86, s87
	v_mfma_f32_16x16x32_bf16 v[120:123], v[140:143], v[182:185], v[120:123]
	v_mfma_f32_16x16x32_bf16 v[112:115], v[132:135], v[190:193], v[112:115]
	v_mfma_f32_16x16x32_bf16 v[108:111], v[140:143], v[190:193], v[108:111]
	v_mfma_f32_16x16x32_bf16 v[96:99], v[132:135], v[206:209], v[96:99]
	v_mfma_f32_16x16x32_bf16 v[92:95], v[140:143], v[206:209], v[92:95]
	v_mfma_f32_16x16x32_bf16 v[80:83], v[132:135], v[214:217], v[80:83]
	v_mfma_f32_16x16x32_bf16 v[76:79], v[140:143], v[214:217], v[76:79]
	v_mfma_f32_16x16x32_bf16 v[116:119], v[160:163], v[178:181], v[116:119]
	v_mfma_f32_16x16x32_bf16 v[104:107], v[168:171], v[178:181], v[104:107]
	v_mfma_f32_16x16x32_bf16 v[100:103], v[160:163], v[186:189], v[100:103]
	v_mfma_f32_16x16x32_bf16 v[88:91], v[168:171], v[186:189], v[88:91]
	v_mfma_f32_16x16x32_bf16 v[84:87], v[160:163], v[194:197], v[84:87]
	v_mfma_f32_16x16x32_bf16 v[72:75], v[168:171], v[194:197], v[72:75]
	v_mfma_f32_16x16x32_bf16 v[68:71], v[160:163], v[210:213], v[68:71]
	v_mfma_f32_16x16x32_bf16 v[64:67], v[168:171], v[210:213], v[64:67]
	v_mfma_f32_16x16x32_bf16 v[116:119], v[164:167], v[182:185], v[116:119]
	v_mfma_f32_16x16x32_bf16 v[104:107], v[172:175], v[182:185], v[104:107]
	v_mfma_f32_16x16x32_bf16 v[100:103], v[164:167], v[190:193], v[100:103]
	v_mfma_f32_16x16x32_bf16 v[88:91], v[172:175], v[190:193], v[88:91]
	v_mfma_f32_16x16x32_bf16 v[84:87], v[164:167], v[206:209], v[84:87]
	v_mfma_f32_16x16x32_bf16 v[72:75], v[172:175], v[206:209], v[72:75]
	v_mfma_f32_16x16x32_bf16 v[68:71], v[164:167], v[214:217], v[68:71]
	s_setprio 0
	v_mfma_f32_16x16x32_bf16 v[64:67], v[172:175], v[214:217], v[64:67]
	s_barrier
	ds_read_b128 v[178:181], v159 offset:16384
	ds_read_b128 v[182:185], v159 offset:17408
	ds_read_b128 v[186:189], v159 offset:18432
	ds_read_b128 v[190:193], v159 offset:19456
	ds_read_b128 v[194:197], v159 offset:20480
	ds_read_b128 v[206:209], v159 offset:21504
	ds_read_b128 v[210:213], v159 offset:22528
	ds_read_b128 v[214:217], v159 offset:23552
	s_add_i32 s0, s79, s65
	s_mov_b32 m0, s0
	v_lshl_add_u64 v[152:153], s[60:61], 0, v[146:147]
	global_load_lds_dwordx4 v[152:153], off
	s_add_i32 m0, s0, 0x2000
	s_add_u32 s0, s60, 0x160000
	v_lshl_add_u64 v[198:199], s[60:61], 0, v[144:145]
	s_addc_u32 s1, s61, 0
	s_add_i32 s2, s80, s65
	global_load_lds_dwordx4 v[198:199], off
	v_lshl_add_u64 v[202:203], s[0:1], 0, v[146:147]
	s_mov_b32 m0, s2
	v_lshl_add_u64 v[218:219], s[62:63], 0, v[144:145]
	global_load_lds_dwordx4 v[202:203], off
	s_add_i32 m0, s2, 0x2000
	v_lshl_add_u64 v[202:203], s[0:1], 0, v[144:145]
	global_load_lds_dwordx4 v[202:203], off
	s_mov_b32 m0, s66
	v_lshl_add_u64 v[202:203], s[62:63], 0, v[146:147]
	global_load_lds_dwordx4 v[202:203], off
	s_mov_b32 m0, s67
	s_nop 0
	global_load_lds_dwordx4 v[218:219], off
	s_waitcnt vmcnt(8) lgkmcnt(0)
	s_setprio 1
	s_barrier
	v_mfma_f32_16x16x32_bf16 v[60:63], v[128:131], v[178:181], v[60:63]
	v_mfma_f32_16x16x32_bf16 v[56:59], v[136:139], v[178:181], v[56:59]
	v_mfma_f32_16x16x32_bf16 v[48:51], v[128:131], v[186:189], v[48:51]
	v_mfma_f32_16x16x32_bf16 v[44:47], v[136:139], v[186:189], v[44:47]
	v_mfma_f32_16x16x32_bf16 v[32:35], v[128:131], v[194:197], v[32:35]
	v_mfma_f32_16x16x32_bf16 v[28:31], v[136:139], v[194:197], v[28:31]
	v_mfma_f32_16x16x32_bf16 v[16:19], v[128:131], v[210:213], v[16:19]
	v_mfma_f32_16x16x32_bf16 v[12:15], v[136:139], v[210:213], v[12:15]
	v_mfma_f32_16x16x32_bf16 v[60:63], v[132:135], v[182:185], v[60:63]
	v_mfma_f32_16x16x32_bf16 v[56:59], v[140:143], v[182:185], v[56:59]
	v_mfma_f32_16x16x32_bf16 v[48:51], v[132:135], v[190:193], v[48:51]
	v_mfma_f32_16x16x32_bf16 v[44:47], v[140:143], v[190:193], v[44:47]
	v_mfma_f32_16x16x32_bf16 v[32:35], v[132:135], v[206:209], v[32:35]
	v_mfma_f32_16x16x32_bf16 v[28:31], v[140:143], v[206:209], v[28:31]
	v_mfma_f32_16x16x32_bf16 v[16:19], v[132:135], v[214:217], v[16:19]
	v_mfma_f32_16x16x32_bf16 v[12:15], v[140:143], v[214:217], v[12:15]
	v_mfma_f32_16x16x32_bf16 v[52:55], v[160:163], v[178:181], v[52:55]
	v_mfma_f32_16x16x32_bf16 v[40:43], v[168:171], v[178:181], v[40:43]
	v_mfma_f32_16x16x32_bf16 v[36:39], v[160:163], v[186:189], v[36:39]
	v_mfma_f32_16x16x32_bf16 v[24:27], v[168:171], v[186:189], v[24:27]
	v_mfma_f32_16x16x32_bf16 v[20:23], v[160:163], v[194:197], v[20:23]
	v_mfma_f32_16x16x32_bf16 v[8:11], v[168:171], v[194:197], v[8:11]
	v_mfma_f32_16x16x32_bf16 v[4:7], v[160:163], v[210:213], v[4:7]
	v_mfma_f32_16x16x32_bf16 v[0:3], v[168:171], v[210:213], v[0:3]
	v_mfma_f32_16x16x32_bf16 v[52:55], v[164:167], v[182:185], v[52:55]
	v_mfma_f32_16x16x32_bf16 v[40:43], v[172:175], v[182:185], v[40:43]
	v_mfma_f32_16x16x32_bf16 v[36:39], v[164:167], v[190:193], v[36:39]
	v_mfma_f32_16x16x32_bf16 v[24:27], v[172:175], v[190:193], v[24:27]
	v_mfma_f32_16x16x32_bf16 v[20:23], v[164:167], v[206:209], v[20:23]
	v_mfma_f32_16x16x32_bf16 v[8:11], v[172:175], v[206:209], v[8:11]
	v_mfma_f32_16x16x32_bf16 v[4:7], v[164:167], v[214:217], v[4:7]
	s_setprio 0
	v_mfma_f32_16x16x32_bf16 v[0:3], v[172:175], v[214:217], v[0:3]
	s_barrier
	ds_read_b128 v[178:181], v159 offset:32768
	ds_read_b128 v[182:185], v159 offset:33792
	ds_read_b128 v[186:189], v159 offset:34816
	ds_read_b128 v[190:193], v159 offset:35840
	ds_read_b128 v[194:197], v159 offset:36864
	ds_read_b128 v[206:209], v159 offset:37888
	ds_read_b128 v[210:213], v159 offset:38912
	ds_read_b128 v[214:217], v159 offset:39936
	s_add_i32 s2, 0, 0x18000
	s_add_i32 s3, 0, 0x1c000
	v_add_u32_e32 v140, s2, v156
	v_add_u32_e32 v172, s3, v156
	ds_read_b128 v[128:131], v140
	ds_read_b128 v[132:135], v140 offset:1024
	ds_read_b128 v[136:139], v140 offset:2048
	ds_read_b128 v[140:143], v140 offset:3072
	ds_read_b128 v[160:163], v172
	ds_read_b128 v[164:167], v172 offset:1024
	ds_read_b128 v[168:171], v172 offset:2048
	ds_read_b128 v[172:175], v172 offset:3072
	s_add_u32 s0, s62, 0x160000
	s_addc_u32 s1, s63, 0
	s_mov_b32 m0, s68
	v_lshl_add_u64 v[220:221], s[0:1], 0, v[146:147]
	global_load_lds_dwordx4 v[220:221], off
	s_mov_b32 m0, s69
	v_lshl_add_u64 v[220:221], s[0:1], 0, v[144:145]
	global_load_lds_dwordx4 v[220:221], off
	s_waitcnt vmcnt(8) lgkmcnt(0)
	s_setprio 1
	s_barrier
	v_mfma_f32_16x16x32_bf16 v[124:127], v[128:131], v[178:181], v[124:127]
	v_mfma_f32_16x16x32_bf16 v[120:123], v[136:139], v[178:181], v[120:123]
	v_mfma_f32_16x16x32_bf16 v[112:115], v[128:131], v[186:189], v[112:115]
	v_mfma_f32_16x16x32_bf16 v[108:111], v[136:139], v[186:189], v[108:111]
	v_mfma_f32_16x16x32_bf16 v[96:99], v[128:131], v[194:197], v[96:99]
	v_mfma_f32_16x16x32_bf16 v[92:95], v[136:139], v[194:197], v[92:95]
	v_mfma_f32_16x16x32_bf16 v[80:83], v[128:131], v[210:213], v[80:83]
	v_mfma_f32_16x16x32_bf16 v[76:79], v[136:139], v[210:213], v[76:79]
	v_mfma_f32_16x16x32_bf16 v[124:127], v[132:135], v[182:185], v[124:127]
	v_mfma_f32_16x16x32_bf16 v[120:123], v[140:143], v[182:185], v[120:123]
	v_mfma_f32_16x16x32_bf16 v[112:115], v[132:135], v[190:193], v[112:115]
	v_mfma_f32_16x16x32_bf16 v[108:111], v[140:143], v[190:193], v[108:111]
	v_mfma_f32_16x16x32_bf16 v[96:99], v[132:135], v[206:209], v[96:99]
	v_mfma_f32_16x16x32_bf16 v[92:95], v[140:143], v[206:209], v[92:95]
	v_mfma_f32_16x16x32_bf16 v[80:83], v[132:135], v[214:217], v[80:83]
	v_mfma_f32_16x16x32_bf16 v[76:79], v[140:143], v[214:217], v[76:79]
	v_mfma_f32_16x16x32_bf16 v[116:119], v[160:163], v[178:181], v[116:119]
	v_mfma_f32_16x16x32_bf16 v[104:107], v[168:171], v[178:181], v[104:107]
	v_mfma_f32_16x16x32_bf16 v[100:103], v[160:163], v[186:189], v[100:103]
	v_mfma_f32_16x16x32_bf16 v[88:91], v[168:171], v[186:189], v[88:91]
	v_mfma_f32_16x16x32_bf16 v[84:87], v[160:163], v[194:197], v[84:87]
	v_mfma_f32_16x16x32_bf16 v[72:75], v[168:171], v[194:197], v[72:75]
	v_mfma_f32_16x16x32_bf16 v[68:71], v[160:163], v[210:213], v[68:71]
	v_mfma_f32_16x16x32_bf16 v[64:67], v[168:171], v[210:213], v[64:67]
	v_mfma_f32_16x16x32_bf16 v[116:119], v[164:167], v[182:185], v[116:119]
	v_mfma_f32_16x16x32_bf16 v[104:107], v[172:175], v[182:185], v[104:107]
	v_mfma_f32_16x16x32_bf16 v[100:103], v[164:167], v[190:193], v[100:103]
	v_mfma_f32_16x16x32_bf16 v[88:91], v[172:175], v[190:193], v[88:91]
	v_mfma_f32_16x16x32_bf16 v[84:87], v[164:167], v[206:209], v[84:87]
	v_mfma_f32_16x16x32_bf16 v[72:75], v[172:175], v[206:209], v[72:75]
	v_mfma_f32_16x16x32_bf16 v[68:71], v[164:167], v[214:217], v[68:71]
	s_setprio 0
	v_mfma_f32_16x16x32_bf16 v[64:67], v[172:175], v[214:217], v[64:67]
	s_barrier
	ds_read_b128 v[178:181], v159 offset:49152
	ds_read_b128 v[182:185], v159 offset:50176
	ds_read_b128 v[186:189], v159 offset:51200
	ds_read_b128 v[190:193], v159 offset:52224
	ds_read_b128 v[194:197], v159 offset:53248
	ds_read_b128 v[206:209], v159 offset:54272
	ds_read_b128 v[210:213], v159 offset:55296
	ds_read_b128 v[214:217], v159 offset:56320
	s_add_i32 s0, s2, s65
	s_mov_b32 m0, s0
	v_lshl_add_u64 v[152:153], v[152:153], 0, s[10:11]
	global_load_lds_dwordx4 v[152:153], off
	s_add_i32 m0, s0, 0x2000
	s_add_u32 s0, s60, 0x160080
	v_lshl_add_u64 v[152:153], v[198:199], 0, s[10:11]
	s_addc_u32 s1, s61, 0
	s_add_i32 s2, s3, s65
	global_load_lds_dwordx4 v[152:153], off
	s_mov_b32 m0, s2
	v_lshl_add_u64 v[152:153], s[0:1], 0, v[146:147]
	global_load_lds_dwordx4 v[152:153], off
	s_add_i32 m0, s2, 0x2000
	v_lshl_add_u64 v[152:153], s[0:1], 0, v[144:145]
	global_load_lds_dwordx4 v[152:153], off
	s_mov_b32 m0, s77
	v_lshl_add_u64 v[152:153], v[202:203], 0, s[10:11]
	global_load_lds_dwordx4 v[152:153], off
	s_mov_b32 m0, s78
	v_lshl_add_u64 v[152:153], v[218:219], 0, s[10:11]
	global_load_lds_dwordx4 v[152:153], off
	s_waitcnt vmcnt(8) lgkmcnt(0)
	s_setprio 1
	s_barrier
	v_mfma_f32_16x16x32_bf16 v[60:63], v[128:131], v[178:181], v[60:63]
	v_mfma_f32_16x16x32_bf16 v[56:59], v[136:139], v[178:181], v[56:59]
	v_mfma_f32_16x16x32_bf16 v[48:51], v[128:131], v[186:189], v[48:51]
	v_mfma_f32_16x16x32_bf16 v[44:47], v[136:139], v[186:189], v[44:47]
	v_mfma_f32_16x16x32_bf16 v[32:35], v[128:131], v[194:197], v[32:35]
	v_mfma_f32_16x16x32_bf16 v[28:31], v[136:139], v[194:197], v[28:31]
	v_mfma_f32_16x16x32_bf16 v[16:19], v[128:131], v[210:213], v[16:19]
	v_mfma_f32_16x16x32_bf16 v[12:15], v[136:139], v[210:213], v[12:15]
	v_mfma_f32_16x16x32_bf16 v[60:63], v[132:135], v[182:185], v[60:63]
	v_mfma_f32_16x16x32_bf16 v[56:59], v[140:143], v[182:185], v[56:59]
	v_mfma_f32_16x16x32_bf16 v[48:51], v[132:135], v[190:193], v[48:51]
	v_mfma_f32_16x16x32_bf16 v[44:47], v[140:143], v[190:193], v[44:47]
	v_mfma_f32_16x16x32_bf16 v[32:35], v[132:135], v[206:209], v[32:35]
	v_mfma_f32_16x16x32_bf16 v[28:31], v[140:143], v[206:209], v[28:31]
	v_mfma_f32_16x16x32_bf16 v[16:19], v[132:135], v[214:217], v[16:19]
	v_mfma_f32_16x16x32_bf16 v[12:15], v[140:143], v[214:217], v[12:15]
	v_mfma_f32_16x16x32_bf16 v[52:55], v[160:163], v[178:181], v[52:55]
	v_mfma_f32_16x16x32_bf16 v[40:43], v[168:171], v[178:181], v[40:43]
	v_mfma_f32_16x16x32_bf16 v[36:39], v[160:163], v[186:189], v[36:39]
	v_mfma_f32_16x16x32_bf16 v[24:27], v[168:171], v[186:189], v[24:27]
	v_mfma_f32_16x16x32_bf16 v[20:23], v[160:163], v[194:197], v[20:23]
	v_mfma_f32_16x16x32_bf16 v[8:11], v[168:171], v[194:197], v[8:11]
	v_mfma_f32_16x16x32_bf16 v[4:7], v[160:163], v[210:213], v[4:7]
	v_mfma_f32_16x16x32_bf16 v[0:3], v[168:171], v[210:213], v[0:3]
	v_mfma_f32_16x16x32_bf16 v[52:55], v[164:167], v[182:185], v[52:55]
	v_mfma_f32_16x16x32_bf16 v[40:43], v[172:175], v[182:185], v[40:43]
	s_add_i32 s89, s89, 2
	v_mfma_f32_16x16x32_bf16 v[36:39], v[164:167], v[190:193], v[36:39]
	s_add_u32 s87, s87, 0x100
	v_mfma_f32_16x16x32_bf16 v[24:27], v[172:175], v[190:193], v[24:27]
	s_addc_u32 s88, s88, 0
	v_mfma_f32_16x16x32_bf16 v[20:23], v[164:167], v[206:209], v[20:23]
	s_cmpk_gt_u32 s89, 0x55
	v_mfma_f32_16x16x32_bf16 v[8:11], v[172:175], v[206:209], v[8:11]
	s_mov_b64 s[56:57], s[58:59]
	v_mfma_f32_16x16x32_bf16 v[4:7], v[164:167], v[214:217], v[4:7]
	s_setprio 0
	v_mfma_f32_16x16x32_bf16 v[0:3], v[172:175], v[214:217], v[0:3]
	s_barrier
	s_cbranch_scc0 .LBB0_541
	s_and_b64 vcc, exec, s[14:15]
	s_cbranch_vccz .LBB0_544
	s_barrier

.LBB0_666:
	ds_read_b128 v[140:143], v147
	ds_read_b128 v[150:153], v147 offset:1024
	ds_read_b128 v[154:157], v147 offset:2048
	ds_read_b128 v[158:161], v147 offset:3072
	ds_read_b128 v[162:165], v148
	ds_read_b128 v[166:169], v148 offset:1024
	ds_read_b128 v[170:173], v148 offset:2048
	ds_read_b128 v[178:181], v148 offset:3072
	ds_read_b128 v[182:185], v149
	ds_read_b128 v[186:189], v149 offset:1024
	ds_read_b128 v[190:193], v149 offset:2048
	ds_read_b128 v[194:197], v149 offset:3072
	ds_read_b128 v[206:209], v149 offset:4096
	ds_read_b128 v[210:213], v149 offset:5120
	ds_read_b128 v[214:217], v149 offset:6144
	ds_read_b128 v[218:221], v149 offset:7168
	s_add_i32 m0, s27, 0xc000
	v_lshl_add_u64 v[174:175], s[28:29], 0, v[136:137]
	global_load_lds_dwordx4 v[174:175], off
	s_add_i32 m0, s27, 0xe000
	v_lshl_add_u64 v[174:175], s[28:29], 0, v[138:139]
	global_load_lds_dwordx4 v[174:175], off
	s_waitcnt vmcnt(8) lgkmcnt(0)
	s_setprio 1
	s_barrier
	v_mfma_f32_16x16x32_bf16 v[124:127], v[140:143], v[182:185], v[124:127]
	v_mfma_f32_16x16x32_bf16 v[120:123], v[154:157], v[182:185], v[120:123]
	v_mfma_f32_16x16x32_bf16 v[116:119], v[140:143], v[190:193], v[116:119]
	s_add_u32 s0, s28, 0xfff80080
	v_mfma_f32_16x16x32_bf16 v[108:111], v[154:157], v[190:193], v[108:111]
	s_addc_u32 s1, s29, -1
	v_mfma_f32_16x16x32_bf16 v[100:103], v[140:143], v[206:209], v[100:103]
	s_cmp_eq_u32 s71, 28
	v_mfma_f32_16x16x32_bf16 v[92:95], v[154:157], v[206:209], v[92:95]
	s_cselect_b32 s35, s15, s1
	v_mfma_f32_16x16x32_bf16 v[84:87], v[140:143], v[214:217], v[84:87]
	s_cselect_b32 s34, s66, s0
	v_mfma_f32_16x16x32_bf16 v[76:79], v[154:157], v[214:217], v[76:79]
	s_cselect_b32 s31, s67, s70
	v_mfma_f32_16x16x32_bf16 v[124:127], v[150:153], v[186:189], v[124:127]
	s_cselect_b32 s30, s68, s69
	v_mfma_f32_16x16x32_bf16 v[120:123], v[158:161], v[186:189], v[120:123]
	v_mfma_f32_16x16x32_bf16 v[116:119], v[150:153], v[194:197], v[116:119]
	v_mfma_f32_16x16x32_bf16 v[108:111], v[158:161], v[194:197], v[108:111]
	v_mfma_f32_16x16x32_bf16 v[100:103], v[150:153], v[210:213], v[100:103]
	v_mfma_f32_16x16x32_bf16 v[92:95], v[158:161], v[210:213], v[92:95]
	v_mfma_f32_16x16x32_bf16 v[84:87], v[150:153], v[218:221], v[84:87]
	v_mfma_f32_16x16x32_bf16 v[76:79], v[158:161], v[218:221], v[76:79]
	v_mfma_f32_16x16x32_bf16 v[112:115], v[162:165], v[182:185], v[112:115]
	v_mfma_f32_16x16x32_bf16 v[104:107], v[170:173], v[182:185], v[104:107]
	v_mfma_f32_16x16x32_bf16 v[96:99], v[162:165], v[190:193], v[96:99]
	v_mfma_f32_16x16x32_bf16 v[88:91], v[170:173], v[190:193], v[88:91]
	v_mfma_f32_16x16x32_bf16 v[80:83], v[162:165], v[206:209], v[80:83]
	v_mfma_f32_16x16x32_bf16 v[72:75], v[170:173], v[206:209], v[72:75]
	v_mfma_f32_16x16x32_bf16 v[68:71], v[162:165], v[214:217], v[68:71]
	v_mfma_f32_16x16x32_bf16 v[64:67], v[170:173], v[214:217], v[64:67]
	v_mfma_f32_16x16x32_bf16 v[112:115], v[166:169], v[186:189], v[112:115]
	v_mfma_f32_16x16x32_bf16 v[104:107], v[178:181], v[186:189], v[104:107]
	v_mfma_f32_16x16x32_bf16 v[96:99], v[166:169], v[194:197], v[96:99]
	v_mfma_f32_16x16x32_bf16 v[88:91], v[178:181], v[194:197], v[88:91]
	v_mfma_f32_16x16x32_bf16 v[80:83], v[166:169], v[210:213], v[80:83]
	v_mfma_f32_16x16x32_bf16 v[72:75], v[178:181], v[210:213], v[72:75]
	v_mfma_f32_16x16x32_bf16 v[68:71], v[166:169], v[218:221], v[68:71]
	s_setprio 0
	v_mfma_f32_16x16x32_bf16 v[64:67], v[178:181], v[218:221], v[64:67]
	s_barrier
	ds_read_b128 v[182:185], v149 offset:16384
	ds_read_b128 v[186:189], v149 offset:17408
	ds_read_b128 v[190:193], v149 offset:18432
	ds_read_b128 v[194:197], v149 offset:19456
	ds_read_b128 v[206:209], v149 offset:20480
	ds_read_b128 v[210:213], v149 offset:21504
	ds_read_b128 v[214:217], v149 offset:22528
	ds_read_b128 v[218:221], v149 offset:23552
	s_add_i32 s0, s62, s53
	s_mov_b32 m0, s0
	v_lshl_add_u64 v[174:175], s[30:31], 0, v[132:133]
	global_load_lds_dwordx4 v[174:175], off
	s_add_i32 m0, s0, 0x2000
	s_add_u32 s0, s30, 0x80000
	v_lshl_add_u64 v[198:199], s[30:31], 0, v[128:129]
	s_addc_u32 s1, s31, 0
	s_add_i32 s2, s63, s53
	global_load_lds_dwordx4 v[198:199], off
	v_lshl_add_u64 v[202:203], s[0:1], 0, v[132:133]
	s_mov_b32 m0, s2
	v_lshl_add_u64 v[222:223], s[34:35], 0, v[130:131]
	global_load_lds_dwordx4 v[202:203], off
	s_add_i32 m0, s2, 0x2000
	v_lshl_add_u64 v[202:203], s[0:1], 0, v[128:129]
	global_load_lds_dwordx4 v[202:203], off
	s_mov_b32 m0, s27
	v_lshl_add_u64 v[202:203], s[34:35], 0, v[134:135]
	global_load_lds_dwordx4 v[202:203], off
	s_mov_b32 m0, s55
	s_nop 0
	global_load_lds_dwordx4 v[222:223], off
	s_waitcnt vmcnt(8) lgkmcnt(0)
	s_setprio 1
	s_barrier
	v_mfma_f32_16x16x32_bf16 v[60:63], v[140:143], v[182:185], v[60:63]
	v_mfma_f32_16x16x32_bf16 v[56:59], v[154:157], v[182:185], v[56:59]
	v_mfma_f32_16x16x32_bf16 v[52:55], v[140:143], v[190:193], v[52:55]
	v_mfma_f32_16x16x32_bf16 v[44:47], v[154:157], v[190:193], v[44:47]
	v_mfma_f32_16x16x32_bf16 v[36:39], v[140:143], v[206:209], v[36:39]
	v_mfma_f32_16x16x32_bf16 v[28:31], v[154:157], v[206:209], v[28:31]
	v_mfma_f32_16x16x32_bf16 v[20:23], v[140:143], v[214:217], v[20:23]
	v_mfma_f32_16x16x32_bf16 v[12:15], v[154:157], v[214:217], v[12:15]
	v_mfma_f32_16x16x32_bf16 v[60:63], v[150:153], v[186:189], v[60:63]
	v_mfma_f32_16x16x32_bf16 v[56:59], v[158:161], v[186:189], v[56:59]
	v_mfma_f32_16x16x32_bf16 v[52:55], v[150:153], v[194:197], v[52:55]
	v_mfma_f32_16x16x32_bf16 v[44:47], v[158:161], v[194:197], v[44:47]
	v_mfma_f32_16x16x32_bf16 v[36:39], v[150:153], v[210:213], v[36:39]
	v_mfma_f32_16x16x32_bf16 v[28:31], v[158:161], v[210:213], v[28:31]
	v_mfma_f32_16x16x32_bf16 v[20:23], v[150:153], v[218:221], v[20:23]
	v_mfma_f32_16x16x32_bf16 v[12:15], v[158:161], v[218:221], v[12:15]
	v_mfma_f32_16x16x32_bf16 v[48:51], v[162:165], v[182:185], v[48:51]
	v_mfma_f32_16x16x32_bf16 v[40:43], v[170:173], v[182:185], v[40:43]
	v_mfma_f32_16x16x32_bf16 v[32:35], v[162:165], v[190:193], v[32:35]
	v_mfma_f32_16x16x32_bf16 v[24:27], v[170:173], v[190:193], v[24:27]
	v_mfma_f32_16x16x32_bf16 v[16:19], v[162:165], v[206:209], v[16:19]
	v_mfma_f32_16x16x32_bf16 v[8:11], v[170:173], v[206:209], v[8:11]
	v_mfma_f32_16x16x32_bf16 v[4:7], v[162:165], v[214:217], v[4:7]
	v_mfma_f32_16x16x32_bf16 v[0:3], v[170:173], v[214:217], v[0:3]
	v_mfma_f32_16x16x32_bf16 v[48:51], v[166:169], v[186:189], v[48:51]
	v_mfma_f32_16x16x32_bf16 v[40:43], v[178:181], v[186:189], v[40:43]
	v_mfma_f32_16x16x32_bf16 v[32:35], v[166:169], v[194:197], v[32:35]
	v_mfma_f32_16x16x32_bf16 v[24:27], v[178:181], v[194:197], v[24:27]
	v_mfma_f32_16x16x32_bf16 v[16:19], v[166:169], v[210:213], v[16:19]
	v_mfma_f32_16x16x32_bf16 v[8:11], v[178:181], v[210:213], v[8:11]
	v_mfma_f32_16x16x32_bf16 v[4:7], v[166:169], v[218:221], v[4:7]
	s_setprio 0
	v_mfma_f32_16x16x32_bf16 v[0:3], v[178:181], v[218:221], v[0:3]
	s_barrier
	ds_read_b128 v[182:185], v149 offset:32768
	ds_read_b128 v[186:189], v149 offset:33792
	ds_read_b128 v[190:193], v149 offset:34816
	ds_read_b128 v[194:197], v149 offset:35840
	ds_read_b128 v[206:209], v149 offset:36864
	ds_read_b128 v[210:213], v149 offset:37888
	ds_read_b128 v[214:217], v149 offset:38912
	ds_read_b128 v[218:221], v149 offset:39936
	s_add_i32 s2, 0, 0x18000
	s_add_i32 s3, 0, 0x1c000
	v_add_u32_e32 v158, s2, v146
	v_add_u32_e32 v177, s3, v146
	ds_read_b128 v[140:143], v158
	ds_read_b128 v[150:153], v158 offset:1024
	ds_read_b128 v[154:157], v158 offset:2048
	ds_read_b128 v[158:161], v158 offset:3072
	ds_read_b128 v[162:165], v177
	ds_read_b128 v[166:169], v177 offset:1024
	ds_read_b128 v[170:173], v177 offset:2048
	ds_read_b128 v[178:181], v177 offset:3072
	s_add_u32 s0, s34, 0x80000
	s_addc_u32 s1, s35, 0
	s_mov_b32 m0, s56
	v_lshl_add_u64 v[224:225], s[0:1], 0, v[134:135]
	global_load_lds_dwordx4 v[224:225], off
	s_mov_b32 m0, s57
	v_lshl_add_u64 v[224:225], s[0:1], 0, v[130:131]
	global_load_lds_dwordx4 v[224:225], off
	s_waitcnt vmcnt(8) lgkmcnt(0)
	s_setprio 1
	s_barrier
	v_mfma_f32_16x16x32_bf16 v[124:127], v[140:143], v[182:185], v[124:127]
	v_mfma_f32_16x16x32_bf16 v[120:123], v[154:157], v[182:185], v[120:123]
	v_mfma_f32_16x16x32_bf16 v[116:119], v[140:143], v[190:193], v[116:119]
	v_mfma_f32_16x16x32_bf16 v[108:111], v[154:157], v[190:193], v[108:111]
	v_mfma_f32_16x16x32_bf16 v[100:103], v[140:143], v[206:209], v[100:103]
	v_mfma_f32_16x16x32_bf16 v[92:95], v[154:157], v[206:209], v[92:95]
	v_mfma_f32_16x16x32_bf16 v[84:87], v[140:143], v[214:217], v[84:87]
	v_mfma_f32_16x16x32_bf16 v[76:79], v[154:157], v[214:217], v[76:79]
	v_mfma_f32_16x16x32_bf16 v[124:127], v[150:153], v[186:189], v[124:127]
	v_mfma_f32_16x16x32_bf16 v[120:123], v[158:161], v[186:189], v[120:123]
	v_mfma_f32_16x16x32_bf16 v[116:119], v[150:153], v[194:197], v[116:119]
	v_mfma_f32_16x16x32_bf16 v[108:111], v[158:161], v[194:197], v[108:111]
	v_mfma_f32_16x16x32_bf16 v[100:103], v[150:153], v[210:213], v[100:103]
	v_mfma_f32_16x16x32_bf16 v[92:95], v[158:161], v[210:213], v[92:95]
	v_mfma_f32_16x16x32_bf16 v[84:87], v[150:153], v[218:221], v[84:87]
	v_mfma_f32_16x16x32_bf16 v[76:79], v[158:161], v[218:221], v[76:79]
	v_mfma_f32_16x16x32_bf16 v[112:115], v[162:165], v[182:185], v[112:115]
	v_mfma_f32_16x16x32_bf16 v[104:107], v[170:173], v[182:185], v[104:107]
	v_mfma_f32_16x16x32_bf16 v[96:99], v[162:165], v[190:193], v[96:99]
	v_mfma_f32_16x16x32_bf16 v[88:91], v[170:173], v[190:193], v[88:91]
	v_mfma_f32_16x16x32_bf16 v[80:83], v[162:165], v[206:209], v[80:83]
	v_mfma_f32_16x16x32_bf16 v[72:75], v[170:173], v[206:209], v[72:75]
	v_mfma_f32_16x16x32_bf16 v[68:71], v[162:165], v[214:217], v[68:71]
	v_mfma_f32_16x16x32_bf16 v[64:67], v[170:173], v[214:217], v[64:67]
	v_mfma_f32_16x16x32_bf16 v[112:115], v[166:169], v[186:189], v[112:115]
	v_mfma_f32_16x16x32_bf16 v[104:107], v[178:181], v[186:189], v[104:107]
	v_mfma_f32_16x16x32_bf16 v[96:99], v[166:169], v[194:197], v[96:99]
	v_mfma_f32_16x16x32_bf16 v[88:91], v[178:181], v[194:197], v[88:91]
	v_mfma_f32_16x16x32_bf16 v[80:83], v[166:169], v[210:213], v[80:83]
	v_mfma_f32_16x16x32_bf16 v[72:75], v[178:181], v[210:213], v[72:75]
	v_mfma_f32_16x16x32_bf16 v[68:71], v[166:169], v[218:221], v[68:71]
	s_setprio 0
	v_mfma_f32_16x16x32_bf16 v[64:67], v[178:181], v[218:221], v[64:67]
	s_barrier
	ds_read_b128 v[182:185], v149 offset:49152
	ds_read_b128 v[186:189], v149 offset:50176
	ds_read_b128 v[190:193], v149 offset:51200
	ds_read_b128 v[194:197], v149 offset:52224
	ds_read_b128 v[206:209], v149 offset:53248
	ds_read_b128 v[210:213], v149 offset:54272
	ds_read_b128 v[214:217], v149 offset:55296
	ds_read_b128 v[218:221], v149 offset:56320
	s_add_i32 s0, s2, s53
	s_mov_b32 m0, s0
	v_lshl_add_u64 v[174:175], v[174:175], 0, s[8:9]
	global_load_lds_dwordx4 v[174:175], off
	s_add_i32 m0, s0, 0x2000
	s_add_u32 s0, s30, 0x80080
	v_lshl_add_u64 v[174:175], v[198:199], 0, s[8:9]
	s_addc_u32 s1, s31, 0
	s_add_i32 s2, s3, s53
	global_load_lds_dwordx4 v[174:175], off
	s_mov_b32 m0, s2
	v_lshl_add_u64 v[174:175], s[0:1], 0, v[132:133]
	global_load_lds_dwordx4 v[174:175], off
	s_add_i32 m0, s2, 0x2000
	v_lshl_add_u64 v[174:175], s[0:1], 0, v[128:129]
	global_load_lds_dwordx4 v[174:175], off
	s_mov_b32 m0, s60
	v_lshl_add_u64 v[174:175], v[202:203], 0, s[8:9]
	global_load_lds_dwordx4 v[174:175], off
	s_mov_b32 m0, s61
	v_lshl_add_u64 v[174:175], v[222:223], 0, s[8:9]
	global_load_lds_dwordx4 v[174:175], off
	s_waitcnt vmcnt(8) lgkmcnt(0)
	s_setprio 1
	s_barrier
	v_mfma_f32_16x16x32_bf16 v[60:63], v[140:143], v[182:185], v[60:63]
	v_mfma_f32_16x16x32_bf16 v[56:59], v[154:157], v[182:185], v[56:59]
	v_mfma_f32_16x16x32_bf16 v[52:55], v[140:143], v[190:193], v[52:55]
	v_mfma_f32_16x16x32_bf16 v[44:47], v[154:157], v[190:193], v[44:47]
	v_mfma_f32_16x16x32_bf16 v[36:39], v[140:143], v[206:209], v[36:39]
	v_mfma_f32_16x16x32_bf16 v[28:31], v[154:157], v[206:209], v[28:31]
	v_mfma_f32_16x16x32_bf16 v[20:23], v[140:143], v[214:217], v[20:23]
	v_mfma_f32_16x16x32_bf16 v[12:15], v[154:157], v[214:217], v[12:15]
	v_mfma_f32_16x16x32_bf16 v[60:63], v[150:153], v[186:189], v[60:63]
	v_mfma_f32_16x16x32_bf16 v[56:59], v[158:161], v[186:189], v[56:59]
	v_mfma_f32_16x16x32_bf16 v[52:55], v[150:153], v[194:197], v[52:55]
	v_mfma_f32_16x16x32_bf16 v[44:47], v[158:161], v[194:197], v[44:47]
	v_mfma_f32_16x16x32_bf16 v[36:39], v[150:153], v[210:213], v[36:39]
	v_mfma_f32_16x16x32_bf16 v[28:31], v[158:161], v[210:213], v[28:31]
	v_mfma_f32_16x16x32_bf16 v[20:23], v[150:153], v[218:221], v[20:23]
	v_mfma_f32_16x16x32_bf16 v[12:15], v[158:161], v[218:221], v[12:15]
	v_mfma_f32_16x16x32_bf16 v[48:51], v[162:165], v[182:185], v[48:51]
	v_mfma_f32_16x16x32_bf16 v[40:43], v[170:173], v[182:185], v[40:43]
	v_mfma_f32_16x16x32_bf16 v[32:35], v[162:165], v[190:193], v[32:35]
	v_mfma_f32_16x16x32_bf16 v[24:27], v[170:173], v[190:193], v[24:27]
	v_mfma_f32_16x16x32_bf16 v[16:19], v[162:165], v[206:209], v[16:19]
	v_mfma_f32_16x16x32_bf16 v[8:11], v[170:173], v[206:209], v[8:11]
	v_mfma_f32_16x16x32_bf16 v[4:7], v[162:165], v[214:217], v[4:7]
	v_mfma_f32_16x16x32_bf16 v[0:3], v[170:173], v[214:217], v[0:3]
	v_mfma_f32_16x16x32_bf16 v[48:51], v[166:169], v[186:189], v[48:51]
	s_add_i32 s71, s71, 2
	v_mfma_f32_16x16x32_bf16 v[40:43], v[178:181], v[186:189], v[40:43]
	s_add_u32 s28, s28, 0x100
	v_mfma_f32_16x16x32_bf16 v[32:35], v[166:169], v[194:197], v[32:35]
	s_addc_u32 s29, s29, 0
	v_mfma_f32_16x16x32_bf16 v[24:27], v[178:181], v[194:197], v[24:27]
	s_add_u32 s69, s69, 0x100
	v_mfma_f32_16x16x32_bf16 v[16:19], v[166:169], v[210:213], v[16:19]
	s_addc_u32 s70, s70, 0
	v_mfma_f32_16x16x32_bf16 v[8:11], v[178:181], v[210:213], v[8:11]
	s_cmp_gt_u32 s71, 29
	v_mfma_f32_16x16x32_bf16 v[4:7], v[166:169], v[218:221], v[4:7]
	s_setprio 0
	v_mfma_f32_16x16x32_bf16 v[0:3], v[178:181], v[218:221], v[0:3]
	s_barrier
	s_cbranch_scc0 .LBB0_666
	s_and_b64 vcc, exec, s[12:13]
	s_cbranch_vccz .LBB0_669
	s_barrier

.LBB0_953:
	ds_read_b128 v[148:151], v145
	ds_read_b128 v[152:155], v145 offset:1024
	ds_read_b128 v[156:159], v145 offset:2048
	ds_read_b128 v[160:163], v145 offset:3072
	ds_read_b128 v[164:167], v146
	ds_read_b128 v[168:171], v146 offset:1024
	ds_read_b128 v[172:175], v146 offset:2048
	ds_read_b128 v[178:181], v146 offset:3072
	ds_read_b128 v[182:185], v147
	ds_read_b128 v[186:189], v147 offset:1024
	ds_read_b128 v[190:193], v147 offset:2048
	ds_read_b128 v[194:197], v147 offset:3072
	ds_read_b128 v[206:209], v147 offset:4096
	ds_read_b128 v[210:213], v147 offset:5120
	ds_read_b128 v[214:217], v147 offset:6144
	ds_read_b128 v[218:221], v147 offset:7168
	s_add_i32 m0, s67, 0xc000
	v_lshl_add_u64 v[140:141], s[54:55], 0, v[136:137]
	global_load_lds_dwordx4 v[140:141], off
	s_add_i32 m0, s67, 0xe000
	v_lshl_add_u64 v[140:141], s[54:55], 0, v[138:139]
	global_load_lds_dwordx4 v[140:141], off
	s_waitcnt vmcnt(8) lgkmcnt(0)
	s_setprio 1
	s_barrier
	v_mfma_f32_16x16x32_bf16 v[124:127], v[148:151], v[182:185], v[124:127]
	v_mfma_f32_16x16x32_bf16 v[120:123], v[156:159], v[182:185], v[120:123]
	v_mfma_f32_16x16x32_bf16 v[116:119], v[148:151], v[190:193], v[116:119]
	s_add_u32 s56, s54, 0x100
	v_mfma_f32_16x16x32_bf16 v[108:111], v[156:159], v[190:193], v[108:111]
	s_addc_u32 s57, s55, 0
	v_mfma_f32_16x16x32_bf16 v[100:103], v[148:151], v[206:209], v[100:103]
	s_cmp_eq_u32 vcc_hi, 20
	v_mfma_f32_16x16x32_bf16 v[92:95], v[156:159], v[206:209], v[92:95]
	s_cselect_b32 s61, s93, s57
	v_mfma_f32_16x16x32_bf16 v[84:87], v[148:151], v[214:217], v[84:87]
	s_cselect_b32 s60, s94, s56
	v_mfma_f32_16x16x32_bf16 v[76:79], v[156:159], v[214:217], v[76:79]
	s_cselect_b32 s59, s95, vcc_lo
	v_mfma_f32_16x16x32_bf16 v[124:127], v[152:155], v[186:189], v[124:127]
	s_cselect_b32 s58, s96, s97
	v_mfma_f32_16x16x32_bf16 v[120:123], v[160:163], v[186:189], v[120:123]
	v_mfma_f32_16x16x32_bf16 v[116:119], v[152:155], v[194:197], v[116:119]
	v_mfma_f32_16x16x32_bf16 v[108:111], v[160:163], v[194:197], v[108:111]
	v_mfma_f32_16x16x32_bf16 v[100:103], v[152:155], v[210:213], v[100:103]
	v_mfma_f32_16x16x32_bf16 v[92:95], v[160:163], v[210:213], v[92:95]
	v_mfma_f32_16x16x32_bf16 v[84:87], v[152:155], v[218:221], v[84:87]
	v_mfma_f32_16x16x32_bf16 v[76:79], v[160:163], v[218:221], v[76:79]
	v_mfma_f32_16x16x32_bf16 v[112:115], v[164:167], v[182:185], v[112:115]
	v_mfma_f32_16x16x32_bf16 v[104:107], v[172:175], v[182:185], v[104:107]
	v_mfma_f32_16x16x32_bf16 v[96:99], v[164:167], v[190:193], v[96:99]
	v_mfma_f32_16x16x32_bf16 v[88:91], v[172:175], v[190:193], v[88:91]
	v_mfma_f32_16x16x32_bf16 v[80:83], v[164:167], v[206:209], v[80:83]
	v_mfma_f32_16x16x32_bf16 v[72:75], v[172:175], v[206:209], v[72:75]
	v_mfma_f32_16x16x32_bf16 v[68:71], v[164:167], v[214:217], v[68:71]
	v_mfma_f32_16x16x32_bf16 v[64:67], v[172:175], v[214:217], v[64:67]
	v_mfma_f32_16x16x32_bf16 v[112:115], v[168:171], v[186:189], v[112:115]
	v_mfma_f32_16x16x32_bf16 v[104:107], v[178:181], v[186:189], v[104:107]
	v_mfma_f32_16x16x32_bf16 v[96:99], v[168:171], v[194:197], v[96:99]
	v_mfma_f32_16x16x32_bf16 v[88:91], v[178:181], v[194:197], v[88:91]
	v_mfma_f32_16x16x32_bf16 v[80:83], v[168:171], v[210:213], v[80:83]
	v_mfma_f32_16x16x32_bf16 v[72:75], v[178:181], v[210:213], v[72:75]
	v_mfma_f32_16x16x32_bf16 v[68:71], v[168:171], v[218:221], v[68:71]
	s_setprio 0
	v_mfma_f32_16x16x32_bf16 v[64:67], v[178:181], v[218:221], v[64:67]
	s_barrier
	ds_read_b128 v[182:185], v147 offset:16384
	ds_read_b128 v[186:189], v147 offset:17408
	ds_read_b128 v[190:193], v147 offset:18432
	ds_read_b128 v[194:197], v147 offset:19456
	ds_read_b128 v[206:209], v147 offset:20480
	ds_read_b128 v[210:213], v147 offset:21504
	ds_read_b128 v[214:217], v147 offset:22528
	ds_read_b128 v[218:221], v147 offset:23552
	s_add_i32 s0, s79, s66
	s_mov_b32 m0, s0
	v_lshl_add_u64 v[140:141], s[58:59], 0, v[130:131]
	global_load_lds_dwordx4 v[140:141], off
	s_add_i32 m0, s0, 0x2000
	s_add_u32 s0, s58, 0x60000
	v_lshl_add_u64 v[198:199], s[58:59], 0, v[134:135]
	s_addc_u32 s1, s59, 0
	s_add_i32 s2, s80, s66
	global_load_lds_dwordx4 v[198:199], off
	v_lshl_add_u64 v[202:203], s[0:1], 0, v[130:131]
	s_mov_b32 m0, s2
	v_lshl_add_u64 v[222:223], s[60:61], 0, v[132:133]
	global_load_lds_dwordx4 v[202:203], off
	s_add_i32 m0, s2, 0x2000
	v_lshl_add_u64 v[202:203], s[0:1], 0, v[134:135]
	global_load_lds_dwordx4 v[202:203], off
	s_mov_b32 m0, s67
	v_lshl_add_u64 v[202:203], s[60:61], 0, v[128:129]
	global_load_lds_dwordx4 v[202:203], off
	s_mov_b32 m0, s68
	s_nop 0
	global_load_lds_dwordx4 v[222:223], off
	s_waitcnt vmcnt(8) lgkmcnt(0)
	s_setprio 1
	s_barrier
	v_mfma_f32_16x16x32_bf16 v[60:63], v[148:151], v[182:185], v[60:63]
	v_mfma_f32_16x16x32_bf16 v[56:59], v[156:159], v[182:185], v[56:59]
	v_mfma_f32_16x16x32_bf16 v[52:55], v[148:151], v[190:193], v[52:55]
	v_mfma_f32_16x16x32_bf16 v[44:47], v[156:159], v[190:193], v[44:47]
	v_mfma_f32_16x16x32_bf16 v[36:39], v[148:151], v[206:209], v[36:39]
	v_mfma_f32_16x16x32_bf16 v[28:31], v[156:159], v[206:209], v[28:31]
	v_mfma_f32_16x16x32_bf16 v[20:23], v[148:151], v[214:217], v[20:23]
	v_mfma_f32_16x16x32_bf16 v[12:15], v[156:159], v[214:217], v[12:15]
	v_mfma_f32_16x16x32_bf16 v[60:63], v[152:155], v[186:189], v[60:63]
	v_mfma_f32_16x16x32_bf16 v[56:59], v[160:163], v[186:189], v[56:59]
	v_mfma_f32_16x16x32_bf16 v[52:55], v[152:155], v[194:197], v[52:55]
	v_mfma_f32_16x16x32_bf16 v[44:47], v[160:163], v[194:197], v[44:47]
	v_mfma_f32_16x16x32_bf16 v[36:39], v[152:155], v[210:213], v[36:39]
	v_mfma_f32_16x16x32_bf16 v[28:31], v[160:163], v[210:213], v[28:31]
	v_mfma_f32_16x16x32_bf16 v[20:23], v[152:155], v[218:221], v[20:23]
	v_mfma_f32_16x16x32_bf16 v[12:15], v[160:163], v[218:221], v[12:15]
	v_mfma_f32_16x16x32_bf16 v[48:51], v[164:167], v[182:185], v[48:51]
	v_mfma_f32_16x16x32_bf16 v[40:43], v[172:175], v[182:185], v[40:43]
	v_mfma_f32_16x16x32_bf16 v[32:35], v[164:167], v[190:193], v[32:35]
	v_mfma_f32_16x16x32_bf16 v[24:27], v[172:175], v[190:193], v[24:27]
	v_mfma_f32_16x16x32_bf16 v[16:19], v[164:167], v[206:209], v[16:19]
	v_mfma_f32_16x16x32_bf16 v[8:11], v[172:175], v[206:209], v[8:11]
	v_mfma_f32_16x16x32_bf16 v[4:7], v[164:167], v[214:217], v[4:7]
	v_mfma_f32_16x16x32_bf16 v[0:3], v[172:175], v[214:217], v[0:3]
	v_mfma_f32_16x16x32_bf16 v[48:51], v[168:171], v[186:189], v[48:51]
	v_mfma_f32_16x16x32_bf16 v[40:43], v[178:181], v[186:189], v[40:43]
	v_mfma_f32_16x16x32_bf16 v[32:35], v[168:171], v[194:197], v[32:35]
	v_mfma_f32_16x16x32_bf16 v[24:27], v[178:181], v[194:197], v[24:27]
	v_mfma_f32_16x16x32_bf16 v[16:19], v[168:171], v[210:213], v[16:19]
	v_mfma_f32_16x16x32_bf16 v[8:11], v[178:181], v[210:213], v[8:11]
	v_mfma_f32_16x16x32_bf16 v[4:7], v[168:171], v[218:221], v[4:7]
	s_setprio 0
	v_mfma_f32_16x16x32_bf16 v[0:3], v[178:181], v[218:221], v[0:3]
	s_barrier
	ds_read_b128 v[182:185], v147 offset:32768
	ds_read_b128 v[186:189], v147 offset:33792
	ds_read_b128 v[190:193], v147 offset:34816
	ds_read_b128 v[194:197], v147 offset:35840
	ds_read_b128 v[206:209], v147 offset:36864
	ds_read_b128 v[210:213], v147 offset:37888
	ds_read_b128 v[214:217], v147 offset:38912
	ds_read_b128 v[218:221], v147 offset:39936
	s_add_i32 s2, 0, 0x18000
	s_add_i32 s3, 0, 0x1c000
	v_add_u32_e32 v160, s2, v144
	v_add_u32_e32 v177, s3, v144
	ds_read_b128 v[148:151], v160
	ds_read_b128 v[152:155], v160 offset:1024
	ds_read_b128 v[156:159], v160 offset:2048
	ds_read_b128 v[160:163], v160 offset:3072
	ds_read_b128 v[164:167], v177
	ds_read_b128 v[168:171], v177 offset:1024
	ds_read_b128 v[172:175], v177 offset:2048
	ds_read_b128 v[178:181], v177 offset:3072
	s_add_u32 s0, s60, 0x60000
	s_addc_u32 s1, s61, 0
	s_mov_b32 m0, s69
	v_lshl_add_u64 v[224:225], s[0:1], 0, v[128:129]
	global_load_lds_dwordx4 v[224:225], off
	s_mov_b32 m0, s70
	v_lshl_add_u64 v[224:225], s[0:1], 0, v[132:133]
	global_load_lds_dwordx4 v[224:225], off
	s_waitcnt vmcnt(8) lgkmcnt(0)
	s_setprio 1
	s_barrier
	v_mfma_f32_16x16x32_bf16 v[124:127], v[148:151], v[182:185], v[124:127]
	v_mfma_f32_16x16x32_bf16 v[120:123], v[156:159], v[182:185], v[120:123]
	v_mfma_f32_16x16x32_bf16 v[116:119], v[148:151], v[190:193], v[116:119]
	v_mfma_f32_16x16x32_bf16 v[108:111], v[156:159], v[190:193], v[108:111]
	v_mfma_f32_16x16x32_bf16 v[100:103], v[148:151], v[206:209], v[100:103]
	v_mfma_f32_16x16x32_bf16 v[92:95], v[156:159], v[206:209], v[92:95]
	v_mfma_f32_16x16x32_bf16 v[84:87], v[148:151], v[214:217], v[84:87]
	v_mfma_f32_16x16x32_bf16 v[76:79], v[156:159], v[214:217], v[76:79]
	v_mfma_f32_16x16x32_bf16 v[124:127], v[152:155], v[186:189], v[124:127]
	v_mfma_f32_16x16x32_bf16 v[120:123], v[160:163], v[186:189], v[120:123]
	v_mfma_f32_16x16x32_bf16 v[116:119], v[152:155], v[194:197], v[116:119]
	v_mfma_f32_16x16x32_bf16 v[108:111], v[160:163], v[194:197], v[108:111]
	v_mfma_f32_16x16x32_bf16 v[100:103], v[152:155], v[210:213], v[100:103]
	v_mfma_f32_16x16x32_bf16 v[92:95], v[160:163], v[210:213], v[92:95]
	v_mfma_f32_16x16x32_bf16 v[84:87], v[152:155], v[218:221], v[84:87]
	v_mfma_f32_16x16x32_bf16 v[76:79], v[160:163], v[218:221], v[76:79]
	v_mfma_f32_16x16x32_bf16 v[112:115], v[164:167], v[182:185], v[112:115]
	v_mfma_f32_16x16x32_bf16 v[104:107], v[172:175], v[182:185], v[104:107]
	v_mfma_f32_16x16x32_bf16 v[96:99], v[164:167], v[190:193], v[96:99]
	v_mfma_f32_16x16x32_bf16 v[88:91], v[172:175], v[190:193], v[88:91]
	v_mfma_f32_16x16x32_bf16 v[80:83], v[164:167], v[206:209], v[80:83]
	v_mfma_f32_16x16x32_bf16 v[72:75], v[172:175], v[206:209], v[72:75]
	v_mfma_f32_16x16x32_bf16 v[68:71], v[164:167], v[214:217], v[68:71]
	v_mfma_f32_16x16x32_bf16 v[64:67], v[172:175], v[214:217], v[64:67]
	v_mfma_f32_16x16x32_bf16 v[112:115], v[168:171], v[186:189], v[112:115]
	v_mfma_f32_16x16x32_bf16 v[104:107], v[178:181], v[186:189], v[104:107]
	v_mfma_f32_16x16x32_bf16 v[96:99], v[168:171], v[194:197], v[96:99]
	v_mfma_f32_16x16x32_bf16 v[88:91], v[178:181], v[194:197], v[88:91]
	v_mfma_f32_16x16x32_bf16 v[80:83], v[168:171], v[210:213], v[80:83]
	v_mfma_f32_16x16x32_bf16 v[72:75], v[178:181], v[210:213], v[72:75]
	v_mfma_f32_16x16x32_bf16 v[68:71], v[168:171], v[218:221], v[68:71]
	s_setprio 0
	v_mfma_f32_16x16x32_bf16 v[64:67], v[178:181], v[218:221], v[64:67]
	s_barrier
	ds_read_b128 v[182:185], v147 offset:49152
	ds_read_b128 v[186:189], v147 offset:50176
	ds_read_b128 v[190:193], v147 offset:51200
	ds_read_b128 v[194:197], v147 offset:52224
	ds_read_b128 v[206:209], v147 offset:53248
	ds_read_b128 v[210:213], v147 offset:54272
	ds_read_b128 v[214:217], v147 offset:55296
	ds_read_b128 v[218:221], v147 offset:56320
	s_add_i32 s0, s2, s66
	s_mov_b32 m0, s0
	v_lshl_add_u64 v[140:141], v[140:141], 0, s[12:13]
	global_load_lds_dwordx4 v[140:141], off
	s_add_i32 m0, s0, 0x2000
	s_add_u32 s0, s58, 0x60080
	v_lshl_add_u64 v[140:141], v[198:199], 0, s[12:13]
	s_addc_u32 s1, s59, 0
	s_add_i32 s2, s3, s66
	global_load_lds_dwordx4 v[140:141], off
	s_mov_b32 m0, s2
	v_lshl_add_u64 v[140:141], s[0:1], 0, v[130:131]
	global_load_lds_dwordx4 v[140:141], off
	s_add_i32 m0, s2, 0x2000
	v_lshl_add_u64 v[140:141], s[0:1], 0, v[134:135]
	global_load_lds_dwordx4 v[140:141], off
	s_mov_b32 m0, s77
	v_lshl_add_u64 v[140:141], v[202:203], 0, s[12:13]
	global_load_lds_dwordx4 v[140:141], off
	s_mov_b32 m0, s78
	v_lshl_add_u64 v[140:141], v[222:223], 0, s[12:13]
	global_load_lds_dwordx4 v[140:141], off
	s_waitcnt vmcnt(8) lgkmcnt(0)
	s_setprio 1
	s_barrier
	v_mfma_f32_16x16x32_bf16 v[60:63], v[148:151], v[182:185], v[60:63]
	v_mfma_f32_16x16x32_bf16 v[56:59], v[156:159], v[182:185], v[56:59]
	v_mfma_f32_16x16x32_bf16 v[52:55], v[148:151], v[190:193], v[52:55]
	v_mfma_f32_16x16x32_bf16 v[44:47], v[156:159], v[190:193], v[44:47]
	v_mfma_f32_16x16x32_bf16 v[36:39], v[148:151], v[206:209], v[36:39]
	v_mfma_f32_16x16x32_bf16 v[28:31], v[156:159], v[206:209], v[28:31]
	v_mfma_f32_16x16x32_bf16 v[20:23], v[148:151], v[214:217], v[20:23]
	v_mfma_f32_16x16x32_bf16 v[12:15], v[156:159], v[214:217], v[12:15]
	v_mfma_f32_16x16x32_bf16 v[60:63], v[152:155], v[186:189], v[60:63]
	v_mfma_f32_16x16x32_bf16 v[56:59], v[160:163], v[186:189], v[56:59]
	v_mfma_f32_16x16x32_bf16 v[52:55], v[152:155], v[194:197], v[52:55]
	v_mfma_f32_16x16x32_bf16 v[44:47], v[160:163], v[194:197], v[44:47]
	v_mfma_f32_16x16x32_bf16 v[36:39], v[152:155], v[210:213], v[36:39]
	v_mfma_f32_16x16x32_bf16 v[28:31], v[160:163], v[210:213], v[28:31]
	v_mfma_f32_16x16x32_bf16 v[20:23], v[152:155], v[218:221], v[20:23]
	v_mfma_f32_16x16x32_bf16 v[12:15], v[160:163], v[218:221], v[12:15]
	v_mfma_f32_16x16x32_bf16 v[48:51], v[164:167], v[182:185], v[48:51]
	v_mfma_f32_16x16x32_bf16 v[40:43], v[172:175], v[182:185], v[40:43]
	v_mfma_f32_16x16x32_bf16 v[32:35], v[164:167], v[190:193], v[32:35]
	v_mfma_f32_16x16x32_bf16 v[24:27], v[172:175], v[190:193], v[24:27]
	v_mfma_f32_16x16x32_bf16 v[16:19], v[164:167], v[206:209], v[16:19]
	v_mfma_f32_16x16x32_bf16 v[8:11], v[172:175], v[206:209], v[8:11]
	v_mfma_f32_16x16x32_bf16 v[4:7], v[164:167], v[214:217], v[4:7]
	v_mfma_f32_16x16x32_bf16 v[0:3], v[172:175], v[214:217], v[0:3]
	v_mfma_f32_16x16x32_bf16 v[48:51], v[168:171], v[186:189], v[48:51]
	v_mfma_f32_16x16x32_bf16 v[40:43], v[178:181], v[186:189], v[40:43]
	s_add_i32 vcc_hi, vcc_hi, 2
	v_mfma_f32_16x16x32_bf16 v[32:35], v[168:171], v[194:197], v[32:35]
	s_add_u32 s97, s97, 0x100
	v_mfma_f32_16x16x32_bf16 v[24:27], v[178:181], v[194:197], v[24:27]
	s_addc_u32 vcc_lo, vcc_lo, 0
	v_mfma_f32_16x16x32_bf16 v[16:19], v[168:171], v[210:213], v[16:19]
	s_cmp_gt_u32 vcc_hi, 21
	v_mfma_f32_16x16x32_bf16 v[8:11], v[178:181], v[210:213], v[8:11]
	s_mov_b64 s[54:55], s[56:57]
	v_mfma_f32_16x16x32_bf16 v[4:7], v[168:171], v[218:221], v[4:7]
	s_setprio 0
	v_mfma_f32_16x16x32_bf16 v[0:3], v[178:181], v[218:221], v[0:3]
	s_barrier
	s_cbranch_scc0 .LBB0_953
	s_and_b64 vcc, exec, s[14:15]
	s_cbranch_vccz .LBB0_956
	s_barrier

.LBB0_1037:
	ds_read_b128 v[128:131], v157
	ds_read_b128 v[132:135], v157 offset:1024
	ds_read_b128 v[136:139], v157 offset:2048
	ds_read_b128 v[140:143], v157 offset:3072
	ds_read_b128 v[160:163], v158
	ds_read_b128 v[164:167], v158 offset:1024
	ds_read_b128 v[168:171], v158 offset:2048
	ds_read_b128 v[172:175], v158 offset:3072
	ds_read_b128 v[178:181], v159
	ds_read_b128 v[182:185], v159 offset:1024
	ds_read_b128 v[186:189], v159 offset:2048
	ds_read_b128 v[190:193], v159 offset:3072
	ds_read_b128 v[194:197], v159 offset:4096
	ds_read_b128 v[206:209], v159 offset:5120
	ds_read_b128 v[210:213], v159 offset:6144
	ds_read_b128 v[214:217], v159 offset:7168
	s_add_i32 m0, s68, 0xc000
	v_lshl_add_u64 v[152:153], s[58:59], 0, v[148:149]
	global_load_lds_dwordx4 v[152:153], off
	s_add_i32 m0, s68, 0xe000
	v_lshl_add_u64 v[152:153], s[58:59], 0, v[150:151]
	global_load_lds_dwordx4 v[152:153], off
	s_waitcnt vmcnt(8) lgkmcnt(0)
	s_setprio 1
	s_barrier
	v_mfma_f32_16x16x32_bf16 v[124:127], v[128:131], v[178:181], v[124:127]
	v_mfma_f32_16x16x32_bf16 v[120:123], v[136:139], v[178:181], v[120:123]
	v_mfma_f32_16x16x32_bf16 v[112:115], v[128:131], v[186:189], v[112:115]
	s_add_u32 s0, s58, 0xfff00080
	v_mfma_f32_16x16x32_bf16 v[108:111], v[136:139], v[186:189], v[108:111]
	s_addc_u32 s1, s59, -1
	v_mfma_f32_16x16x32_bf16 v[96:99], v[128:131], v[194:197], v[96:99]
	s_cmp_eq_u32 s87, 60
	v_mfma_f32_16x16x32_bf16 v[92:95], v[136:139], v[194:197], v[92:95]
	s_cselect_b32 s63, s12, s1
	v_mfma_f32_16x16x32_bf16 v[80:83], v[128:131], v[210:213], v[80:83]
	s_cselect_b32 s62, s29, s0
	v_mfma_f32_16x16x32_bf16 v[76:79], v[136:139], v[210:213], v[76:79]
	s_cselect_b32 s61, s57, s86
	v_mfma_f32_16x16x32_bf16 v[124:127], v[132:135], v[182:185], v[124:127]
	s_cselect_b32 s60, s64, s65
	v_mfma_f32_16x16x32_bf16 v[120:123], v[140:143], v[182:185], v[120:123]
	v_mfma_f32_16x16x32_bf16 v[112:115], v[132:135], v[190:193], v[112:115]
	v_mfma_f32_16x16x32_bf16 v[108:111], v[140:143], v[190:193], v[108:111]
	v_mfma_f32_16x16x32_bf16 v[96:99], v[132:135], v[206:209], v[96:99]
	v_mfma_f32_16x16x32_bf16 v[92:95], v[140:143], v[206:209], v[92:95]
	v_mfma_f32_16x16x32_bf16 v[80:83], v[132:135], v[214:217], v[80:83]
	v_mfma_f32_16x16x32_bf16 v[76:79], v[140:143], v[214:217], v[76:79]
	v_mfma_f32_16x16x32_bf16 v[116:119], v[160:163], v[178:181], v[116:119]
	v_mfma_f32_16x16x32_bf16 v[104:107], v[168:171], v[178:181], v[104:107]
	v_mfma_f32_16x16x32_bf16 v[100:103], v[160:163], v[186:189], v[100:103]
	v_mfma_f32_16x16x32_bf16 v[88:91], v[168:171], v[186:189], v[88:91]
	v_mfma_f32_16x16x32_bf16 v[84:87], v[160:163], v[194:197], v[84:87]
	v_mfma_f32_16x16x32_bf16 v[72:75], v[168:171], v[194:197], v[72:75]
	v_mfma_f32_16x16x32_bf16 v[68:71], v[160:163], v[210:213], v[68:71]
	v_mfma_f32_16x16x32_bf16 v[64:67], v[168:171], v[210:213], v[64:67]
	v_mfma_f32_16x16x32_bf16 v[116:119], v[164:167], v[182:185], v[116:119]
	v_mfma_f32_16x16x32_bf16 v[104:107], v[172:175], v[182:185], v[104:107]
	v_mfma_f32_16x16x32_bf16 v[100:103], v[164:167], v[190:193], v[100:103]
	v_mfma_f32_16x16x32_bf16 v[88:91], v[172:175], v[190:193], v[88:91]
	v_mfma_f32_16x16x32_bf16 v[84:87], v[164:167], v[206:209], v[84:87]
	v_mfma_f32_16x16x32_bf16 v[72:75], v[172:175], v[206:209], v[72:75]
	v_mfma_f32_16x16x32_bf16 v[68:71], v[164:167], v[214:217], v[68:71]
	s_setprio 0
	v_mfma_f32_16x16x32_bf16 v[64:67], v[172:175], v[214:217], v[64:67]
	s_barrier
	ds_read_b128 v[178:181], v159 offset:16384
	ds_read_b128 v[182:185], v159 offset:17408
	ds_read_b128 v[186:189], v159 offset:18432
	ds_read_b128 v[190:193], v159 offset:19456
	ds_read_b128 v[194:197], v159 offset:20480
	ds_read_b128 v[206:209], v159 offset:21504
	ds_read_b128 v[210:213], v159 offset:22528
	ds_read_b128 v[214:217], v159 offset:23552
	s_add_i32 s0, s81, s67
	s_mov_b32 m0, s0
	v_lshl_add_u64 v[152:153], s[60:61], 0, v[146:147]
	global_load_lds_dwordx4 v[152:153], off
	s_add_i32 m0, s0, 0x2000
	s_add_u32 s0, s60, 0x100000
	v_lshl_add_u64 v[198:199], s[60:61], 0, v[144:145]
	s_addc_u32 s1, s61, 0
	s_add_i32 s2, s82, s67
	global_load_lds_dwordx4 v[198:199], off
	v_lshl_add_u64 v[202:203], s[0:1], 0, v[146:147]
	s_mov_b32 m0, s2
	v_lshl_add_u64 v[218:219], s[62:63], 0, v[144:145]
	global_load_lds_dwordx4 v[202:203], off
	s_add_i32 m0, s2, 0x2000
	v_lshl_add_u64 v[202:203], s[0:1], 0, v[144:145]
	global_load_lds_dwordx4 v[202:203], off
	s_mov_b32 m0, s68
	v_lshl_add_u64 v[202:203], s[62:63], 0, v[146:147]
	global_load_lds_dwordx4 v[202:203], off
	s_mov_b32 m0, s69
	s_nop 0
	global_load_lds_dwordx4 v[218:219], off
	s_waitcnt vmcnt(8) lgkmcnt(0)
	s_setprio 1
	s_barrier
	v_mfma_f32_16x16x32_bf16 v[60:63], v[128:131], v[178:181], v[60:63]
	v_mfma_f32_16x16x32_bf16 v[56:59], v[136:139], v[178:181], v[56:59]
	v_mfma_f32_16x16x32_bf16 v[48:51], v[128:131], v[186:189], v[48:51]
	v_mfma_f32_16x16x32_bf16 v[44:47], v[136:139], v[186:189], v[44:47]
	v_mfma_f32_16x16x32_bf16 v[32:35], v[128:131], v[194:197], v[32:35]
	v_mfma_f32_16x16x32_bf16 v[28:31], v[136:139], v[194:197], v[28:31]
	v_mfma_f32_16x16x32_bf16 v[16:19], v[128:131], v[210:213], v[16:19]
	v_mfma_f32_16x16x32_bf16 v[12:15], v[136:139], v[210:213], v[12:15]
	v_mfma_f32_16x16x32_bf16 v[60:63], v[132:135], v[182:185], v[60:63]
	v_mfma_f32_16x16x32_bf16 v[56:59], v[140:143], v[182:185], v[56:59]
	v_mfma_f32_16x16x32_bf16 v[48:51], v[132:135], v[190:193], v[48:51]
	v_mfma_f32_16x16x32_bf16 v[44:47], v[140:143], v[190:193], v[44:47]
	v_mfma_f32_16x16x32_bf16 v[32:35], v[132:135], v[206:209], v[32:35]
	v_mfma_f32_16x16x32_bf16 v[28:31], v[140:143], v[206:209], v[28:31]
	v_mfma_f32_16x16x32_bf16 v[16:19], v[132:135], v[214:217], v[16:19]
	v_mfma_f32_16x16x32_bf16 v[12:15], v[140:143], v[214:217], v[12:15]
	v_mfma_f32_16x16x32_bf16 v[52:55], v[160:163], v[178:181], v[52:55]
	v_mfma_f32_16x16x32_bf16 v[40:43], v[168:171], v[178:181], v[40:43]
	v_mfma_f32_16x16x32_bf16 v[36:39], v[160:163], v[186:189], v[36:39]
	v_mfma_f32_16x16x32_bf16 v[24:27], v[168:171], v[186:189], v[24:27]
	v_mfma_f32_16x16x32_bf16 v[20:23], v[160:163], v[194:197], v[20:23]
	v_mfma_f32_16x16x32_bf16 v[8:11], v[168:171], v[194:197], v[8:11]
	v_mfma_f32_16x16x32_bf16 v[4:7], v[160:163], v[210:213], v[4:7]
	v_mfma_f32_16x16x32_bf16 v[0:3], v[168:171], v[210:213], v[0:3]
	v_mfma_f32_16x16x32_bf16 v[52:55], v[164:167], v[182:185], v[52:55]
	v_mfma_f32_16x16x32_bf16 v[40:43], v[172:175], v[182:185], v[40:43]
	v_mfma_f32_16x16x32_bf16 v[36:39], v[164:167], v[190:193], v[36:39]
	v_mfma_f32_16x16x32_bf16 v[24:27], v[172:175], v[190:193], v[24:27]
	v_mfma_f32_16x16x32_bf16 v[20:23], v[164:167], v[206:209], v[20:23]
	v_mfma_f32_16x16x32_bf16 v[8:11], v[172:175], v[206:209], v[8:11]
	v_mfma_f32_16x16x32_bf16 v[4:7], v[164:167], v[214:217], v[4:7]
	s_setprio 0
	v_mfma_f32_16x16x32_bf16 v[0:3], v[172:175], v[214:217], v[0:3]
	s_barrier
	ds_read_b128 v[178:181], v159 offset:32768
	ds_read_b128 v[182:185], v159 offset:33792
	ds_read_b128 v[186:189], v159 offset:34816
	ds_read_b128 v[190:193], v159 offset:35840
	ds_read_b128 v[194:197], v159 offset:36864
	ds_read_b128 v[206:209], v159 offset:37888
	ds_read_b128 v[210:213], v159 offset:38912
	ds_read_b128 v[214:217], v159 offset:39936
	s_add_i32 s2, 0, 0x18000
	s_add_i32 s3, 0, 0x1c000
	v_add_u32_e32 v140, s2, v156
	v_add_u32_e32 v172, s3, v156
	ds_read_b128 v[128:131], v140
	ds_read_b128 v[132:135], v140 offset:1024
	ds_read_b128 v[136:139], v140 offset:2048
	ds_read_b128 v[140:143], v140 offset:3072
	ds_read_b128 v[160:163], v172
	ds_read_b128 v[164:167], v172 offset:1024
	ds_read_b128 v[168:171], v172 offset:2048
	ds_read_b128 v[172:175], v172 offset:3072
	s_add_u32 s0, s62, 0x100000
	s_addc_u32 s1, s63, 0
	s_mov_b32 m0, s70
	v_lshl_add_u64 v[220:221], s[0:1], 0, v[146:147]
	global_load_lds_dwordx4 v[220:221], off
	s_mov_b32 m0, s71
	v_lshl_add_u64 v[220:221], s[0:1], 0, v[144:145]
	global_load_lds_dwordx4 v[220:221], off
	s_waitcnt vmcnt(8) lgkmcnt(0)
	s_setprio 1
	s_barrier
	v_mfma_f32_16x16x32_bf16 v[124:127], v[128:131], v[178:181], v[124:127]
	v_mfma_f32_16x16x32_bf16 v[120:123], v[136:139], v[178:181], v[120:123]
	v_mfma_f32_16x16x32_bf16 v[112:115], v[128:131], v[186:189], v[112:115]
	v_mfma_f32_16x16x32_bf16 v[108:111], v[136:139], v[186:189], v[108:111]
	v_mfma_f32_16x16x32_bf16 v[96:99], v[128:131], v[194:197], v[96:99]
	v_mfma_f32_16x16x32_bf16 v[92:95], v[136:139], v[194:197], v[92:95]
	v_mfma_f32_16x16x32_bf16 v[80:83], v[128:131], v[210:213], v[80:83]
	v_mfma_f32_16x16x32_bf16 v[76:79], v[136:139], v[210:213], v[76:79]
	v_mfma_f32_16x16x32_bf16 v[124:127], v[132:135], v[182:185], v[124:127]
	v_mfma_f32_16x16x32_bf16 v[120:123], v[140:143], v[182:185], v[120:123]
	v_mfma_f32_16x16x32_bf16 v[112:115], v[132:135], v[190:193], v[112:115]
	v_mfma_f32_16x16x32_bf16 v[108:111], v[140:143], v[190:193], v[108:111]
	v_mfma_f32_16x16x32_bf16 v[96:99], v[132:135], v[206:209], v[96:99]
	v_mfma_f32_16x16x32_bf16 v[92:95], v[140:143], v[206:209], v[92:95]
	v_mfma_f32_16x16x32_bf16 v[80:83], v[132:135], v[214:217], v[80:83]
	v_mfma_f32_16x16x32_bf16 v[76:79], v[140:143], v[214:217], v[76:79]
	v_mfma_f32_16x16x32_bf16 v[116:119], v[160:163], v[178:181], v[116:119]
	v_mfma_f32_16x16x32_bf16 v[104:107], v[168:171], v[178:181], v[104:107]
	v_mfma_f32_16x16x32_bf16 v[100:103], v[160:163], v[186:189], v[100:103]
	v_mfma_f32_16x16x32_bf16 v[88:91], v[168:171], v[186:189], v[88:91]
	v_mfma_f32_16x16x32_bf16 v[84:87], v[160:163], v[194:197], v[84:87]
	v_mfma_f32_16x16x32_bf16 v[72:75], v[168:171], v[194:197], v[72:75]
	v_mfma_f32_16x16x32_bf16 v[68:71], v[160:163], v[210:213], v[68:71]
	v_mfma_f32_16x16x32_bf16 v[64:67], v[168:171], v[210:213], v[64:67]
	v_mfma_f32_16x16x32_bf16 v[116:119], v[164:167], v[182:185], v[116:119]
	v_mfma_f32_16x16x32_bf16 v[104:107], v[172:175], v[182:185], v[104:107]
	v_mfma_f32_16x16x32_bf16 v[100:103], v[164:167], v[190:193], v[100:103]
	v_mfma_f32_16x16x32_bf16 v[88:91], v[172:175], v[190:193], v[88:91]
	v_mfma_f32_16x16x32_bf16 v[84:87], v[164:167], v[206:209], v[84:87]
	v_mfma_f32_16x16x32_bf16 v[72:75], v[172:175], v[206:209], v[72:75]
	v_mfma_f32_16x16x32_bf16 v[68:71], v[164:167], v[214:217], v[68:71]
	s_setprio 0
	v_mfma_f32_16x16x32_bf16 v[64:67], v[172:175], v[214:217], v[64:67]
	s_barrier
	ds_read_b128 v[178:181], v159 offset:49152
	ds_read_b128 v[182:185], v159 offset:50176
	ds_read_b128 v[186:189], v159 offset:51200
	ds_read_b128 v[190:193], v159 offset:52224
	ds_read_b128 v[194:197], v159 offset:53248
	ds_read_b128 v[206:209], v159 offset:54272
	ds_read_b128 v[210:213], v159 offset:55296
	ds_read_b128 v[214:217], v159 offset:56320
	s_add_i32 s0, s2, s67
	s_mov_b32 m0, s0
	v_lshl_add_u64 v[152:153], v[152:153], 0, s[10:11]
	global_load_lds_dwordx4 v[152:153], off
	s_add_i32 m0, s0, 0x2000
	s_add_u32 s0, s60, 0x100080
	v_lshl_add_u64 v[152:153], v[198:199], 0, s[10:11]
	s_addc_u32 s1, s61, 0
	s_add_i32 s2, s3, s67
	global_load_lds_dwordx4 v[152:153], off
	s_mov_b32 m0, s2
	v_lshl_add_u64 v[152:153], s[0:1], 0, v[146:147]
	global_load_lds_dwordx4 v[152:153], off
	s_add_i32 m0, s2, 0x2000
	v_lshl_add_u64 v[152:153], s[0:1], 0, v[144:145]
	global_load_lds_dwordx4 v[152:153], off
	s_mov_b32 m0, s79
	v_lshl_add_u64 v[152:153], v[202:203], 0, s[10:11]
	global_load_lds_dwordx4 v[152:153], off
	s_mov_b32 m0, s80
	v_lshl_add_u64 v[152:153], v[218:219], 0, s[10:11]
	global_load_lds_dwordx4 v[152:153], off
	s_waitcnt vmcnt(8) lgkmcnt(0)
	s_setprio 1
	s_barrier
	v_mfma_f32_16x16x32_bf16 v[60:63], v[128:131], v[178:181], v[60:63]
	v_mfma_f32_16x16x32_bf16 v[56:59], v[136:139], v[178:181], v[56:59]
	v_mfma_f32_16x16x32_bf16 v[48:51], v[128:131], v[186:189], v[48:51]
	v_mfma_f32_16x16x32_bf16 v[44:47], v[136:139], v[186:189], v[44:47]
	v_mfma_f32_16x16x32_bf16 v[32:35], v[128:131], v[194:197], v[32:35]
	v_mfma_f32_16x16x32_bf16 v[28:31], v[136:139], v[194:197], v[28:31]
	v_mfma_f32_16x16x32_bf16 v[16:19], v[128:131], v[210:213], v[16:19]
	v_mfma_f32_16x16x32_bf16 v[12:15], v[136:139], v[210:213], v[12:15]
	v_mfma_f32_16x16x32_bf16 v[60:63], v[132:135], v[182:185], v[60:63]
	v_mfma_f32_16x16x32_bf16 v[56:59], v[140:143], v[182:185], v[56:59]
	v_mfma_f32_16x16x32_bf16 v[48:51], v[132:135], v[190:193], v[48:51]
	v_mfma_f32_16x16x32_bf16 v[44:47], v[140:143], v[190:193], v[44:47]
	v_mfma_f32_16x16x32_bf16 v[32:35], v[132:135], v[206:209], v[32:35]
	v_mfma_f32_16x16x32_bf16 v[28:31], v[140:143], v[206:209], v[28:31]
	v_mfma_f32_16x16x32_bf16 v[16:19], v[132:135], v[214:217], v[16:19]
	v_mfma_f32_16x16x32_bf16 v[12:15], v[140:143], v[214:217], v[12:15]
	v_mfma_f32_16x16x32_bf16 v[52:55], v[160:163], v[178:181], v[52:55]
	v_mfma_f32_16x16x32_bf16 v[40:43], v[168:171], v[178:181], v[40:43]
	v_mfma_f32_16x16x32_bf16 v[36:39], v[160:163], v[186:189], v[36:39]
	v_mfma_f32_16x16x32_bf16 v[24:27], v[168:171], v[186:189], v[24:27]
	v_mfma_f32_16x16x32_bf16 v[20:23], v[160:163], v[194:197], v[20:23]
	v_mfma_f32_16x16x32_bf16 v[8:11], v[168:171], v[194:197], v[8:11]
	v_mfma_f32_16x16x32_bf16 v[4:7], v[160:163], v[210:213], v[4:7]
	v_mfma_f32_16x16x32_bf16 v[0:3], v[168:171], v[210:213], v[0:3]
	v_mfma_f32_16x16x32_bf16 v[52:55], v[164:167], v[182:185], v[52:55]
	s_add_i32 s87, s87, 2
	v_mfma_f32_16x16x32_bf16 v[40:43], v[172:175], v[182:185], v[40:43]
	s_add_u32 s58, s58, 0x100
	v_mfma_f32_16x16x32_bf16 v[36:39], v[164:167], v[190:193], v[36:39]
	s_addc_u32 s59, s59, 0
	v_mfma_f32_16x16x32_bf16 v[24:27], v[172:175], v[190:193], v[24:27]
	s_add_u32 s65, s65, 0x100
	v_mfma_f32_16x16x32_bf16 v[20:23], v[164:167], v[206:209], v[20:23]
	s_addc_u32 s86, s86, 0
	v_mfma_f32_16x16x32_bf16 v[8:11], v[172:175], v[206:209], v[8:11]
	s_cmp_gt_u32 s87, 61
	v_mfma_f32_16x16x32_bf16 v[4:7], v[164:167], v[214:217], v[4:7]
	s_setprio 0
	v_mfma_f32_16x16x32_bf16 v[0:3], v[172:175], v[214:217], v[0:3]
	s_barrier
	s_cbranch_scc0 .LBB0_1037
	s_and_b64 vcc, exec, s[14:15]
	s_cbranch_vccz .LBB0_1040
	s_barrier

.LBB0_1107:
	ds_read_b128 v[128:131], v203
	ds_read_b128 v[132:135], v203 offset:1024
	ds_read_b128 v[136:139], v203 offset:2048
	ds_read_b128 v[140:143], v203 offset:3072
	ds_read_b128 v[144:147], v204
	ds_read_b128 v[148:151], v204 offset:1024
	ds_read_b128 v[152:155], v204 offset:2048
	ds_read_b128 v[156:159], v204 offset:3072
	ds_read_b128 v[160:163], v205
	ds_read_b128 v[164:167], v205 offset:1024
	ds_read_b128 v[168:171], v205 offset:2048
	ds_read_b128 v[172:175], v205 offset:3072
	ds_read_b128 v[190:193], v205 offset:4096
	ds_read_b128 v[194:197], v205 offset:5120
	ds_read_b128 v[206:209], v205 offset:6144
	ds_read_b128 v[210:213], v205 offset:7168
	s_add_i32 m0, s77, 0xc000
	v_lshl_add_u64 v[198:199], s[4:5], 0, v[186:187]
	global_load_lds_dwordx4 v[198:199], off
	s_add_i32 m0, s77, 0xe000
	v_lshl_add_u64 v[198:199], s[4:5], 0, v[188:189]
	global_load_lds_dwordx4 v[198:199], off
	s_waitcnt vmcnt(8) lgkmcnt(0)
	s_setprio 1
	s_barrier
	v_mfma_f32_16x16x32_bf16 v[124:127], v[128:131], v[160:163], v[124:127]
	v_mfma_f32_16x16x32_bf16 v[56:59], v[136:139], v[160:163], v[56:59]
	v_mfma_f32_16x16x32_bf16 v[116:119], v[128:131], v[168:171], v[116:119]
	s_add_u32 s0, s4, 0xfff80080
	v_mfma_f32_16x16x32_bf16 v[52:55], v[136:139], v[168:171], v[52:55]
	s_addc_u32 s1, s5, -1
	v_mfma_f32_16x16x32_bf16 v[108:111], v[128:131], v[190:193], v[108:111]
	s_cmp_eq_u32 s96, 28
	v_mfma_f32_16x16x32_bf16 v[44:47], v[136:139], v[190:193], v[44:47]
	s_cselect_b32 s9, s13, s1
	v_mfma_f32_16x16x32_bf16 v[104:107], v[128:131], v[206:209], v[104:107]
	s_cselect_b32 s8, s15, s0
	v_mfma_f32_16x16x32_bf16 v[32:35], v[136:139], v[206:209], v[32:35]
	s_cselect_b32 s7, s37, s11
	v_mfma_f32_16x16x32_bf16 v[124:127], v[132:135], v[164:167], v[124:127]
	s_cselect_b32 s6, s63, s10
	v_mfma_f32_16x16x32_bf16 v[56:59], v[140:143], v[164:167], v[56:59]
	v_mfma_f32_16x16x32_bf16 v[116:119], v[132:135], v[172:175], v[116:119]
	v_mfma_f32_16x16x32_bf16 v[52:55], v[140:143], v[172:175], v[52:55]
	v_mfma_f32_16x16x32_bf16 v[108:111], v[132:135], v[194:197], v[108:111]
	v_mfma_f32_16x16x32_bf16 v[44:47], v[140:143], v[194:197], v[44:47]
	v_mfma_f32_16x16x32_bf16 v[104:107], v[132:135], v[210:213], v[104:107]
	v_mfma_f32_16x16x32_bf16 v[32:35], v[140:143], v[210:213], v[32:35]
	v_mfma_f32_16x16x32_bf16 v[120:123], v[144:147], v[160:163], v[120:123]
	v_mfma_f32_16x16x32_bf16 v[60:63], v[152:155], v[160:163], v[60:63]
	v_mfma_f32_16x16x32_bf16 v[112:115], v[144:147], v[168:171], v[112:115]
	v_mfma_f32_16x16x32_bf16 v[48:51], v[152:155], v[168:171], v[48:51]
	v_mfma_f32_16x16x32_bf16 v[100:103], v[144:147], v[190:193], v[100:103]
	v_mfma_f32_16x16x32_bf16 v[40:43], v[152:155], v[190:193], v[40:43]
	v_mfma_f32_16x16x32_bf16 v[96:99], v[144:147], v[206:209], v[96:99]
	v_mfma_f32_16x16x32_bf16 v[36:39], v[152:155], v[206:209], v[36:39]
	v_mfma_f32_16x16x32_bf16 v[120:123], v[148:151], v[164:167], v[120:123]
	v_mfma_f32_16x16x32_bf16 v[60:63], v[156:159], v[164:167], v[60:63]
	v_mfma_f32_16x16x32_bf16 v[112:115], v[148:151], v[172:175], v[112:115]
	v_mfma_f32_16x16x32_bf16 v[48:51], v[156:159], v[172:175], v[48:51]
	v_mfma_f32_16x16x32_bf16 v[100:103], v[148:151], v[194:197], v[100:103]
	v_mfma_f32_16x16x32_bf16 v[40:43], v[156:159], v[194:197], v[40:43]
	v_mfma_f32_16x16x32_bf16 v[96:99], v[148:151], v[210:213], v[96:99]
	s_setprio 0
	v_mfma_f32_16x16x32_bf16 v[36:39], v[156:159], v[210:213], v[36:39]
	s_barrier
	ds_read_b128 v[160:163], v205 offset:16384
	ds_read_b128 v[164:167], v205 offset:17408
	ds_read_b128 v[168:171], v205 offset:18432
	ds_read_b128 v[172:175], v205 offset:19456
	ds_read_b128 v[190:193], v205 offset:20480
	ds_read_b128 v[194:197], v205 offset:21504
	ds_read_b128 v[206:209], v205 offset:22528
	ds_read_b128 v[210:213], v205 offset:23552
	s_add_i32 s0, s92, s76
	s_mov_b32 m0, s0
	v_lshl_add_u64 v[198:199], s[6:7], 0, v[180:181]
	global_load_lds_dwordx4 v[198:199], off
	s_add_i32 m0, s0, 0x2000
	s_add_u32 s0, s6, 0x80000
	v_lshl_add_u64 v[214:215], s[6:7], 0, v[184:185]
	s_addc_u32 s1, s7, 0
	s_add_i32 s2, s93, s76
	global_load_lds_dwordx4 v[214:215], off
	v_lshl_add_u64 v[216:217], s[0:1], 0, v[180:181]
	s_mov_b32 m0, s2
	v_lshl_add_u64 v[218:219], s[8:9], 0, v[182:183]
	global_load_lds_dwordx4 v[216:217], off
	s_add_i32 m0, s2, 0x2000
	v_lshl_add_u64 v[216:217], s[0:1], 0, v[184:185]
	global_load_lds_dwordx4 v[216:217], off
	s_mov_b32 m0, s77
	v_lshl_add_u64 v[216:217], s[8:9], 0, v[178:179]
	global_load_lds_dwordx4 v[216:217], off
	s_mov_b32 m0, s78
	s_nop 0
	global_load_lds_dwordx4 v[218:219], off
	s_waitcnt vmcnt(8) lgkmcnt(0)
	s_setprio 1
	s_barrier
	v_mfma_f32_16x16x32_bf16 v[92:95], v[128:131], v[160:163], v[92:95]
	v_mfma_f32_16x16x32_bf16 v[24:27], v[136:139], v[160:163], v[24:27]
	v_mfma_f32_16x16x32_bf16 v[84:87], v[128:131], v[168:171], v[84:87]
	v_mfma_f32_16x16x32_bf16 v[20:23], v[136:139], v[168:171], v[20:23]
	v_mfma_f32_16x16x32_bf16 v[76:79], v[128:131], v[190:193], v[76:79]
	v_mfma_f32_16x16x32_bf16 v[12:15], v[136:139], v[190:193], v[12:15]
	v_mfma_f32_16x16x32_bf16 v[72:75], v[128:131], v[206:209], v[72:75]
	v_mfma_f32_16x16x32_bf16 v[0:3], v[136:139], v[206:209], v[0:3]
	v_mfma_f32_16x16x32_bf16 v[92:95], v[132:135], v[164:167], v[92:95]
	v_mfma_f32_16x16x32_bf16 v[24:27], v[140:143], v[164:167], v[24:27]
	v_mfma_f32_16x16x32_bf16 v[84:87], v[132:135], v[172:175], v[84:87]
	v_mfma_f32_16x16x32_bf16 v[20:23], v[140:143], v[172:175], v[20:23]
	v_mfma_f32_16x16x32_bf16 v[76:79], v[132:135], v[194:197], v[76:79]
	v_mfma_f32_16x16x32_bf16 v[12:15], v[140:143], v[194:197], v[12:15]
	v_mfma_f32_16x16x32_bf16 v[72:75], v[132:135], v[210:213], v[72:75]
	v_mfma_f32_16x16x32_bf16 v[0:3], v[140:143], v[210:213], v[0:3]
	v_mfma_f32_16x16x32_bf16 v[88:91], v[144:147], v[160:163], v[88:91]
	v_mfma_f32_16x16x32_bf16 v[28:31], v[152:155], v[160:163], v[28:31]
	v_mfma_f32_16x16x32_bf16 v[80:83], v[144:147], v[168:171], v[80:83]
	v_mfma_f32_16x16x32_bf16 v[16:19], v[152:155], v[168:171], v[16:19]
	v_mfma_f32_16x16x32_bf16 v[68:71], v[144:147], v[190:193], v[68:71]
	v_mfma_f32_16x16x32_bf16 v[8:11], v[152:155], v[190:193], v[8:11]
	v_mfma_f32_16x16x32_bf16 v[64:67], v[144:147], v[206:209], v[64:67]
	v_mfma_f32_16x16x32_bf16 v[4:7], v[152:155], v[206:209], v[4:7]
	v_mfma_f32_16x16x32_bf16 v[88:91], v[148:151], v[164:167], v[88:91]
	v_mfma_f32_16x16x32_bf16 v[28:31], v[156:159], v[164:167], v[28:31]
	v_mfma_f32_16x16x32_bf16 v[80:83], v[148:151], v[172:175], v[80:83]
	v_mfma_f32_16x16x32_bf16 v[16:19], v[156:159], v[172:175], v[16:19]
	v_mfma_f32_16x16x32_bf16 v[68:71], v[148:151], v[194:197], v[68:71]
	v_mfma_f32_16x16x32_bf16 v[8:11], v[156:159], v[194:197], v[8:11]
	v_mfma_f32_16x16x32_bf16 v[64:67], v[148:151], v[210:213], v[64:67]
	s_setprio 0
	v_mfma_f32_16x16x32_bf16 v[4:7], v[156:159], v[210:213], v[4:7]
	s_barrier
	ds_read_b128 v[160:163], v205 offset:32768
	ds_read_b128 v[164:167], v205 offset:33792
	ds_read_b128 v[168:171], v205 offset:34816
	ds_read_b128 v[172:175], v205 offset:35840
	ds_read_b128 v[190:193], v205 offset:36864
	ds_read_b128 v[194:197], v205 offset:37888
	ds_read_b128 v[206:209], v205 offset:38912
	ds_read_b128 v[210:213], v205 offset:39936
	s_add_i32 s2, 0, 0x18000
	s_add_i32 s38, 0, 0x1c000
	v_add_u32_e32 v140, s2, v202
	v_add_u32_e32 v156, s38, v202
	ds_read_b128 v[128:131], v140
	ds_read_b128 v[132:135], v140 offset:1024
	ds_read_b128 v[136:139], v140 offset:2048
	ds_read_b128 v[140:143], v140 offset:3072
	ds_read_b128 v[144:147], v156
	ds_read_b128 v[148:151], v156 offset:1024
	ds_read_b128 v[152:155], v156 offset:2048
	ds_read_b128 v[156:159], v156 offset:3072
	s_add_u32 s0, s8, 0x80000
	s_addc_u32 s1, s9, 0
	s_mov_b32 m0, s79
	v_lshl_add_u64 v[220:221], s[0:1], 0, v[178:179]
	global_load_lds_dwordx4 v[220:221], off
	s_mov_b32 m0, s80
	v_lshl_add_u64 v[220:221], s[0:1], 0, v[182:183]
	global_load_lds_dwordx4 v[220:221], off
	s_waitcnt vmcnt(8) lgkmcnt(0)
	s_setprio 1
	s_barrier
	v_mfma_f32_16x16x32_bf16 v[124:127], v[128:131], v[160:163], v[124:127]
	v_mfma_f32_16x16x32_bf16 v[56:59], v[136:139], v[160:163], v[56:59]
	v_mfma_f32_16x16x32_bf16 v[116:119], v[128:131], v[168:171], v[116:119]
	v_mfma_f32_16x16x32_bf16 v[52:55], v[136:139], v[168:171], v[52:55]
	v_mfma_f32_16x16x32_bf16 v[108:111], v[128:131], v[190:193], v[108:111]
	v_mfma_f32_16x16x32_bf16 v[44:47], v[136:139], v[190:193], v[44:47]
	v_mfma_f32_16x16x32_bf16 v[104:107], v[128:131], v[206:209], v[104:107]
	v_mfma_f32_16x16x32_bf16 v[32:35], v[136:139], v[206:209], v[32:35]
	v_mfma_f32_16x16x32_bf16 v[124:127], v[132:135], v[164:167], v[124:127]
	v_mfma_f32_16x16x32_bf16 v[56:59], v[140:143], v[164:167], v[56:59]
	v_mfma_f32_16x16x32_bf16 v[116:119], v[132:135], v[172:175], v[116:119]
	v_mfma_f32_16x16x32_bf16 v[52:55], v[140:143], v[172:175], v[52:55]
	v_mfma_f32_16x16x32_bf16 v[108:111], v[132:135], v[194:197], v[108:111]
	v_mfma_f32_16x16x32_bf16 v[44:47], v[140:143], v[194:197], v[44:47]
	v_mfma_f32_16x16x32_bf16 v[104:107], v[132:135], v[210:213], v[104:107]
	v_mfma_f32_16x16x32_bf16 v[32:35], v[140:143], v[210:213], v[32:35]
	v_mfma_f32_16x16x32_bf16 v[120:123], v[144:147], v[160:163], v[120:123]
	v_mfma_f32_16x16x32_bf16 v[60:63], v[152:155], v[160:163], v[60:63]
	v_mfma_f32_16x16x32_bf16 v[112:115], v[144:147], v[168:171], v[112:115]
	v_mfma_f32_16x16x32_bf16 v[48:51], v[152:155], v[168:171], v[48:51]
	v_mfma_f32_16x16x32_bf16 v[100:103], v[144:147], v[190:193], v[100:103]
	v_mfma_f32_16x16x32_bf16 v[40:43], v[152:155], v[190:193], v[40:43]
	v_mfma_f32_16x16x32_bf16 v[96:99], v[144:147], v[206:209], v[96:99]
	v_mfma_f32_16x16x32_bf16 v[36:39], v[152:155], v[206:209], v[36:39]
	v_mfma_f32_16x16x32_bf16 v[120:123], v[148:151], v[164:167], v[120:123]
	v_mfma_f32_16x16x32_bf16 v[60:63], v[156:159], v[164:167], v[60:63]
	v_mfma_f32_16x16x32_bf16 v[112:115], v[148:151], v[172:175], v[112:115]
	v_mfma_f32_16x16x32_bf16 v[48:51], v[156:159], v[172:175], v[48:51]
	v_mfma_f32_16x16x32_bf16 v[100:103], v[148:151], v[194:197], v[100:103]
	v_mfma_f32_16x16x32_bf16 v[40:43], v[156:159], v[194:197], v[40:43]
	v_mfma_f32_16x16x32_bf16 v[96:99], v[148:151], v[210:213], v[96:99]
	s_setprio 0
	v_mfma_f32_16x16x32_bf16 v[36:39], v[156:159], v[210:213], v[36:39]
	s_barrier
	ds_read_b128 v[160:163], v205 offset:49152
	ds_read_b128 v[164:167], v205 offset:50176
	ds_read_b128 v[168:171], v205 offset:51200
	ds_read_b128 v[172:175], v205 offset:52224
	ds_read_b128 v[190:193], v205 offset:53248
	ds_read_b128 v[194:197], v205 offset:54272
	ds_read_b128 v[206:209], v205 offset:55296
	ds_read_b128 v[210:213], v205 offset:56320
	s_add_i32 s0, s2, s76
	s_mov_b32 m0, s0
	v_lshl_add_u64 v[198:199], v[198:199], 0, s[24:25]
	global_load_lds_dwordx4 v[198:199], off
	s_add_i32 m0, s0, 0x2000
	s_add_u32 s0, s6, 0x80080
	v_lshl_add_u64 v[198:199], v[214:215], 0, s[24:25]
	s_addc_u32 s1, s7, 0
	s_add_i32 s2, s38, s76
	global_load_lds_dwordx4 v[198:199], off
	s_mov_b32 m0, s2
	v_lshl_add_u64 v[198:199], s[0:1], 0, v[180:181]
	global_load_lds_dwordx4 v[198:199], off
	s_add_i32 m0, s2, 0x2000
	v_lshl_add_u64 v[198:199], s[0:1], 0, v[184:185]
	global_load_lds_dwordx4 v[198:199], off
	s_mov_b32 m0, s86
	v_lshl_add_u64 v[198:199], v[216:217], 0, s[24:25]
	global_load_lds_dwordx4 v[198:199], off
	s_mov_b32 m0, s87
	v_lshl_add_u64 v[198:199], v[218:219], 0, s[24:25]
	global_load_lds_dwordx4 v[198:199], off
	s_waitcnt vmcnt(8) lgkmcnt(0)
	s_setprio 1
	s_barrier
	v_mfma_f32_16x16x32_bf16 v[92:95], v[128:131], v[160:163], v[92:95]
	v_mfma_f32_16x16x32_bf16 v[24:27], v[136:139], v[160:163], v[24:27]
	v_mfma_f32_16x16x32_bf16 v[84:87], v[128:131], v[168:171], v[84:87]
	v_mfma_f32_16x16x32_bf16 v[20:23], v[136:139], v[168:171], v[20:23]
	v_mfma_f32_16x16x32_bf16 v[76:79], v[128:131], v[190:193], v[76:79]
	v_mfma_f32_16x16x32_bf16 v[12:15], v[136:139], v[190:193], v[12:15]
	v_mfma_f32_16x16x32_bf16 v[72:75], v[128:131], v[206:209], v[72:75]
	v_mfma_f32_16x16x32_bf16 v[0:3], v[136:139], v[206:209], v[0:3]
	v_mfma_f32_16x16x32_bf16 v[92:95], v[132:135], v[164:167], v[92:95]
	v_mfma_f32_16x16x32_bf16 v[24:27], v[140:143], v[164:167], v[24:27]
	v_mfma_f32_16x16x32_bf16 v[84:87], v[132:135], v[172:175], v[84:87]
	v_mfma_f32_16x16x32_bf16 v[20:23], v[140:143], v[172:175], v[20:23]
	v_mfma_f32_16x16x32_bf16 v[76:79], v[132:135], v[194:197], v[76:79]
	v_mfma_f32_16x16x32_bf16 v[12:15], v[140:143], v[194:197], v[12:15]
	v_mfma_f32_16x16x32_bf16 v[72:75], v[132:135], v[210:213], v[72:75]
	v_mfma_f32_16x16x32_bf16 v[0:3], v[140:143], v[210:213], v[0:3]
	v_mfma_f32_16x16x32_bf16 v[88:91], v[144:147], v[160:163], v[88:91]
	v_mfma_f32_16x16x32_bf16 v[28:31], v[152:155], v[160:163], v[28:31]
	v_mfma_f32_16x16x32_bf16 v[80:83], v[144:147], v[168:171], v[80:83]
	v_mfma_f32_16x16x32_bf16 v[16:19], v[152:155], v[168:171], v[16:19]
	v_mfma_f32_16x16x32_bf16 v[68:71], v[144:147], v[190:193], v[68:71]
	v_mfma_f32_16x16x32_bf16 v[8:11], v[152:155], v[190:193], v[8:11]
	v_mfma_f32_16x16x32_bf16 v[64:67], v[144:147], v[206:209], v[64:67]
	v_mfma_f32_16x16x32_bf16 v[4:7], v[152:155], v[206:209], v[4:7]
	v_mfma_f32_16x16x32_bf16 v[88:91], v[148:151], v[164:167], v[88:91]
	s_add_i32 s96, s96, 2
	v_mfma_f32_16x16x32_bf16 v[28:31], v[156:159], v[164:167], v[28:31]
	s_add_u32 s4, s4, 0x100
	v_mfma_f32_16x16x32_bf16 v[80:83], v[148:151], v[172:175], v[80:83]
	s_addc_u32 s5, s5, 0
	v_mfma_f32_16x16x32_bf16 v[16:19], v[156:159], v[172:175], v[16:19]
	s_add_u32 s10, s10, 0x100
	v_mfma_f32_16x16x32_bf16 v[68:71], v[148:151], v[194:197], v[68:71]
	s_addc_u32 s11, s11, 0
	v_mfma_f32_16x16x32_bf16 v[8:11], v[156:159], v[194:197], v[8:11]
	s_cmp_gt_u32 s96, 29
	v_mfma_f32_16x16x32_bf16 v[64:67], v[148:151], v[210:213], v[64:67]
	s_setprio 0
	v_mfma_f32_16x16x32_bf16 v[4:7], v[156:159], v[210:213], v[4:7]
	s_barrier
	s_cbranch_scc0 .LBB0_1107
	s_and_b64 vcc, exec, s[26:27]
	s_cbranch_vccz .LBB0_1110
	s_barrier

.LBB0_1249:
	ds_read_b128 v[128:131], v157
	ds_read_b128 v[132:135], v157 offset:1024
	ds_read_b128 v[136:139], v157 offset:2048
	ds_read_b128 v[140:143], v157 offset:3072
	ds_read_b128 v[160:163], v158
	ds_read_b128 v[164:167], v158 offset:1024
	ds_read_b128 v[168:171], v158 offset:2048
	ds_read_b128 v[172:175], v158 offset:3072
	ds_read_b128 v[176:179], v159
	ds_read_b128 v[180:183], v159 offset:1024
	ds_read_b128 v[184:187], v159 offset:2048
	ds_read_b128 v[188:191], v159 offset:3072
	ds_read_b128 v[192:195], v159 offset:4096
	ds_read_b128 v[196:199], v159 offset:5120
	ds_read_b128 v[200:203], v159 offset:6144
	ds_read_b128 v[204:207], v159 offset:7168
	s_add_i32 m0, s52, 0xc000
	v_lshl_add_u64 v[152:153], s[36:37], 0, v[148:149]
	global_load_lds_dwordx4 v[152:153], off
	s_add_i32 m0, s52, 0xe000
	v_lshl_add_u64 v[152:153], s[36:37], 0, v[150:151]
	global_load_lds_dwordx4 v[152:153], off
	s_waitcnt vmcnt(8) lgkmcnt(0)
	s_setprio 1
	s_barrier
	v_mfma_f32_16x16x32_bf16 v[124:127], v[128:131], v[176:179], v[124:127]
	v_mfma_f32_16x16x32_bf16 v[120:123], v[136:139], v[176:179], v[120:123]
	v_mfma_f32_16x16x32_bf16 v[112:115], v[128:131], v[184:187], v[112:115]
	s_add_u32 s38, s36, 0x100
	v_mfma_f32_16x16x32_bf16 v[108:111], v[136:139], v[184:187], v[108:111]
	s_addc_u32 s39, s37, 0
	v_mfma_f32_16x16x32_bf16 v[96:99], v[128:131], v[192:195], v[96:99]
	s_cmpk_eq_i32 s74, 0x54
	v_mfma_f32_16x16x32_bf16 v[92:95], v[136:139], v[192:195], v[92:95]
	s_cselect_b32 s45, s6, s39
	v_mfma_f32_16x16x32_bf16 v[80:83], v[128:131], v[200:203], v[80:83]
	s_cselect_b32 s44, s35, s38
	v_mfma_f32_16x16x32_bf16 v[76:79], v[136:139], v[200:203], v[76:79]
	s_cselect_b32 s43, s70, s73
	v_mfma_f32_16x16x32_bf16 v[124:127], v[132:135], v[180:183], v[124:127]
	s_cselect_b32 s42, s71, s72
	v_mfma_f32_16x16x32_bf16 v[120:123], v[140:143], v[180:183], v[120:123]
	v_mfma_f32_16x16x32_bf16 v[112:115], v[132:135], v[188:191], v[112:115]
	v_mfma_f32_16x16x32_bf16 v[108:111], v[140:143], v[188:191], v[108:111]
	v_mfma_f32_16x16x32_bf16 v[96:99], v[132:135], v[196:199], v[96:99]
	v_mfma_f32_16x16x32_bf16 v[92:95], v[140:143], v[196:199], v[92:95]
	v_mfma_f32_16x16x32_bf16 v[80:83], v[132:135], v[204:207], v[80:83]
	v_mfma_f32_16x16x32_bf16 v[76:79], v[140:143], v[204:207], v[76:79]
	v_mfma_f32_16x16x32_bf16 v[116:119], v[160:163], v[176:179], v[116:119]
	v_mfma_f32_16x16x32_bf16 v[104:107], v[168:171], v[176:179], v[104:107]
	v_mfma_f32_16x16x32_bf16 v[100:103], v[160:163], v[184:187], v[100:103]
	v_mfma_f32_16x16x32_bf16 v[88:91], v[168:171], v[184:187], v[88:91]
	v_mfma_f32_16x16x32_bf16 v[84:87], v[160:163], v[192:195], v[84:87]
	v_mfma_f32_16x16x32_bf16 v[72:75], v[168:171], v[192:195], v[72:75]
	v_mfma_f32_16x16x32_bf16 v[68:71], v[160:163], v[200:203], v[68:71]
	v_mfma_f32_16x16x32_bf16 v[64:67], v[168:171], v[200:203], v[64:67]
	v_mfma_f32_16x16x32_bf16 v[116:119], v[164:167], v[180:183], v[116:119]
	v_mfma_f32_16x16x32_bf16 v[104:107], v[172:175], v[180:183], v[104:107]
	v_mfma_f32_16x16x32_bf16 v[100:103], v[164:167], v[188:191], v[100:103]
	v_mfma_f32_16x16x32_bf16 v[88:91], v[172:175], v[188:191], v[88:91]
	v_mfma_f32_16x16x32_bf16 v[84:87], v[164:167], v[196:199], v[84:87]
	v_mfma_f32_16x16x32_bf16 v[72:75], v[172:175], v[196:199], v[72:75]
	v_mfma_f32_16x16x32_bf16 v[68:71], v[164:167], v[204:207], v[68:71]
	s_setprio 0
	v_mfma_f32_16x16x32_bf16 v[64:67], v[172:175], v[204:207], v[64:67]
	s_barrier
	ds_read_b128 v[176:179], v159 offset:16384
	ds_read_b128 v[180:183], v159 offset:17408
	ds_read_b128 v[184:187], v159 offset:18432
	ds_read_b128 v[188:191], v159 offset:19456
	ds_read_b128 v[192:195], v159 offset:20480
	ds_read_b128 v[196:199], v159 offset:21504
	ds_read_b128 v[200:203], v159 offset:22528
	ds_read_b128 v[204:207], v159 offset:23552
	s_add_i32 s36, s64, s51
	s_mov_b32 m0, s36
	v_lshl_add_u64 v[152:153], s[42:43], 0, v[146:147]
	global_load_lds_dwordx4 v[152:153], off
	s_add_i32 m0, s36, 0x2000
	s_add_u32 s36, s42, 0x160000
	v_lshl_add_u64 v[208:209], s[42:43], 0, v[144:145]
	s_addc_u32 s37, s43, 0
	s_add_i32 s75, s65, s51
	global_load_lds_dwordx4 v[208:209], off
	v_lshl_add_u64 v[210:211], s[36:37], 0, v[146:147]
	s_mov_b32 m0, s75
	v_lshl_add_u64 v[212:213], s[44:45], 0, v[144:145]
	global_load_lds_dwordx4 v[210:211], off
	s_add_i32 m0, s75, 0x2000
	v_lshl_add_u64 v[210:211], s[36:37], 0, v[144:145]
	global_load_lds_dwordx4 v[210:211], off
	s_mov_b32 m0, s52
	v_lshl_add_u64 v[210:211], s[44:45], 0, v[146:147]
	global_load_lds_dwordx4 v[210:211], off
	s_mov_b32 m0, s53
	s_nop 0
	global_load_lds_dwordx4 v[212:213], off
	s_waitcnt vmcnt(8) lgkmcnt(0)
	s_setprio 1
	s_barrier
	v_mfma_f32_16x16x32_bf16 v[60:63], v[128:131], v[176:179], v[60:63]
	v_mfma_f32_16x16x32_bf16 v[56:59], v[136:139], v[176:179], v[56:59]
	v_mfma_f32_16x16x32_bf16 v[48:51], v[128:131], v[184:187], v[48:51]
	v_mfma_f32_16x16x32_bf16 v[44:47], v[136:139], v[184:187], v[44:47]
	v_mfma_f32_16x16x32_bf16 v[32:35], v[128:131], v[192:195], v[32:35]
	v_mfma_f32_16x16x32_bf16 v[28:31], v[136:139], v[192:195], v[28:31]
	v_mfma_f32_16x16x32_bf16 v[16:19], v[128:131], v[200:203], v[16:19]
	v_mfma_f32_16x16x32_bf16 v[12:15], v[136:139], v[200:203], v[12:15]
	v_mfma_f32_16x16x32_bf16 v[60:63], v[132:135], v[180:183], v[60:63]
	v_mfma_f32_16x16x32_bf16 v[56:59], v[140:143], v[180:183], v[56:59]
	v_mfma_f32_16x16x32_bf16 v[48:51], v[132:135], v[188:191], v[48:51]
	v_mfma_f32_16x16x32_bf16 v[44:47], v[140:143], v[188:191], v[44:47]
	v_mfma_f32_16x16x32_bf16 v[32:35], v[132:135], v[196:199], v[32:35]
	v_mfma_f32_16x16x32_bf16 v[28:31], v[140:143], v[196:199], v[28:31]
	v_mfma_f32_16x16x32_bf16 v[16:19], v[132:135], v[204:207], v[16:19]
	v_mfma_f32_16x16x32_bf16 v[12:15], v[140:143], v[204:207], v[12:15]
	v_mfma_f32_16x16x32_bf16 v[52:55], v[160:163], v[176:179], v[52:55]
	v_mfma_f32_16x16x32_bf16 v[40:43], v[168:171], v[176:179], v[40:43]
	v_mfma_f32_16x16x32_bf16 v[36:39], v[160:163], v[184:187], v[36:39]
	v_mfma_f32_16x16x32_bf16 v[24:27], v[168:171], v[184:187], v[24:27]
	v_mfma_f32_16x16x32_bf16 v[20:23], v[160:163], v[192:195], v[20:23]
	v_mfma_f32_16x16x32_bf16 v[8:11], v[168:171], v[192:195], v[8:11]
	v_mfma_f32_16x16x32_bf16 v[4:7], v[160:163], v[200:203], v[4:7]
	v_mfma_f32_16x16x32_bf16 v[0:3], v[168:171], v[200:203], v[0:3]
	v_mfma_f32_16x16x32_bf16 v[52:55], v[164:167], v[180:183], v[52:55]
	v_mfma_f32_16x16x32_bf16 v[40:43], v[172:175], v[180:183], v[40:43]
	v_mfma_f32_16x16x32_bf16 v[36:39], v[164:167], v[188:191], v[36:39]
	v_mfma_f32_16x16x32_bf16 v[24:27], v[172:175], v[188:191], v[24:27]
	v_mfma_f32_16x16x32_bf16 v[20:23], v[164:167], v[196:199], v[20:23]
	v_mfma_f32_16x16x32_bf16 v[8:11], v[172:175], v[196:199], v[8:11]
	v_mfma_f32_16x16x32_bf16 v[4:7], v[164:167], v[204:207], v[4:7]
	s_setprio 0
	v_mfma_f32_16x16x32_bf16 v[0:3], v[172:175], v[204:207], v[0:3]
	s_barrier
	ds_read_b128 v[176:179], v159 offset:32768
	ds_read_b128 v[180:183], v159 offset:33792
	ds_read_b128 v[184:187], v159 offset:34816
	ds_read_b128 v[188:191], v159 offset:35840
	ds_read_b128 v[192:195], v159 offset:36864
	ds_read_b128 v[196:199], v159 offset:37888
	ds_read_b128 v[200:203], v159 offset:38912
	ds_read_b128 v[204:207], v159 offset:39936
	s_add_i32 s75, 0, 0x18000
	s_add_i32 s76, 0, 0x1c000
	v_add_u32_e32 v140, s75, v156
	v_add_u32_e32 v172, s76, v156
	ds_read_b128 v[128:131], v140
	ds_read_b128 v[132:135], v140 offset:1024
	ds_read_b128 v[136:139], v140 offset:2048
	ds_read_b128 v[140:143], v140 offset:3072
	ds_read_b128 v[160:163], v172
	ds_read_b128 v[164:167], v172 offset:1024
	ds_read_b128 v[168:171], v172 offset:2048
	ds_read_b128 v[172:175], v172 offset:3072
	s_add_u32 s36, s44, 0x160000
	s_addc_u32 s37, s45, 0
	s_mov_b32 m0, s54
	v_lshl_add_u64 v[214:215], s[36:37], 0, v[146:147]
	global_load_lds_dwordx4 v[214:215], off
	s_mov_b32 m0, s55
	v_lshl_add_u64 v[214:215], s[36:37], 0, v[144:145]
	global_load_lds_dwordx4 v[214:215], off
	s_waitcnt vmcnt(8) lgkmcnt(0)
	s_setprio 1
	s_barrier
	v_mfma_f32_16x16x32_bf16 v[124:127], v[128:131], v[176:179], v[124:127]
	v_mfma_f32_16x16x32_bf16 v[120:123], v[136:139], v[176:179], v[120:123]
	v_mfma_f32_16x16x32_bf16 v[112:115], v[128:131], v[184:187], v[112:115]
	v_mfma_f32_16x16x32_bf16 v[108:111], v[136:139], v[184:187], v[108:111]
	v_mfma_f32_16x16x32_bf16 v[96:99], v[128:131], v[192:195], v[96:99]
	v_mfma_f32_16x16x32_bf16 v[92:95], v[136:139], v[192:195], v[92:95]
	v_mfma_f32_16x16x32_bf16 v[80:83], v[128:131], v[200:203], v[80:83]
	v_mfma_f32_16x16x32_bf16 v[76:79], v[136:139], v[200:203], v[76:79]
	v_mfma_f32_16x16x32_bf16 v[124:127], v[132:135], v[180:183], v[124:127]
	v_mfma_f32_16x16x32_bf16 v[120:123], v[140:143], v[180:183], v[120:123]
	v_mfma_f32_16x16x32_bf16 v[112:115], v[132:135], v[188:191], v[112:115]
	v_mfma_f32_16x16x32_bf16 v[108:111], v[140:143], v[188:191], v[108:111]
	v_mfma_f32_16x16x32_bf16 v[96:99], v[132:135], v[196:199], v[96:99]
	v_mfma_f32_16x16x32_bf16 v[92:95], v[140:143], v[196:199], v[92:95]
	v_mfma_f32_16x16x32_bf16 v[80:83], v[132:135], v[204:207], v[80:83]
	v_mfma_f32_16x16x32_bf16 v[76:79], v[140:143], v[204:207], v[76:79]
	v_mfma_f32_16x16x32_bf16 v[116:119], v[160:163], v[176:179], v[116:119]
	v_mfma_f32_16x16x32_bf16 v[104:107], v[168:171], v[176:179], v[104:107]
	v_mfma_f32_16x16x32_bf16 v[100:103], v[160:163], v[184:187], v[100:103]
	v_mfma_f32_16x16x32_bf16 v[88:91], v[168:171], v[184:187], v[88:91]
	v_mfma_f32_16x16x32_bf16 v[84:87], v[160:163], v[192:195], v[84:87]
	v_mfma_f32_16x16x32_bf16 v[72:75], v[168:171], v[192:195], v[72:75]
	v_mfma_f32_16x16x32_bf16 v[68:71], v[160:163], v[200:203], v[68:71]
	v_mfma_f32_16x16x32_bf16 v[64:67], v[168:171], v[200:203], v[64:67]
	v_mfma_f32_16x16x32_bf16 v[116:119], v[164:167], v[180:183], v[116:119]
	v_mfma_f32_16x16x32_bf16 v[104:107], v[172:175], v[180:183], v[104:107]
	v_mfma_f32_16x16x32_bf16 v[100:103], v[164:167], v[188:191], v[100:103]
	v_mfma_f32_16x16x32_bf16 v[88:91], v[172:175], v[188:191], v[88:91]
	v_mfma_f32_16x16x32_bf16 v[84:87], v[164:167], v[196:199], v[84:87]
	v_mfma_f32_16x16x32_bf16 v[72:75], v[172:175], v[196:199], v[72:75]
	v_mfma_f32_16x16x32_bf16 v[68:71], v[164:167], v[204:207], v[68:71]
	s_setprio 0
	v_mfma_f32_16x16x32_bf16 v[64:67], v[172:175], v[204:207], v[64:67]
	s_barrier
	ds_read_b128 v[176:179], v159 offset:49152
	ds_read_b128 v[180:183], v159 offset:50176
	ds_read_b128 v[184:187], v159 offset:51200
	ds_read_b128 v[188:191], v159 offset:52224
	ds_read_b128 v[192:195], v159 offset:53248
	ds_read_b128 v[196:199], v159 offset:54272
	ds_read_b128 v[200:203], v159 offset:55296
	ds_read_b128 v[204:207], v159 offset:56320
	s_add_i32 s36, s75, s51
	s_mov_b32 m0, s36
	v_lshl_add_u64 v[152:153], v[152:153], 0, s[4:5]
	global_load_lds_dwordx4 v[152:153], off
	s_add_i32 m0, s36, 0x2000
	s_add_u32 s36, s42, 0x160080
	v_lshl_add_u64 v[152:153], v[208:209], 0, s[4:5]
	s_addc_u32 s37, s43, 0
	s_add_i32 s42, s76, s51
	global_load_lds_dwordx4 v[152:153], off
	s_mov_b32 m0, s42
	v_lshl_add_u64 v[152:153], s[36:37], 0, v[146:147]
	global_load_lds_dwordx4 v[152:153], off
	s_add_i32 m0, s42, 0x2000
	v_lshl_add_u64 v[152:153], s[36:37], 0, v[144:145]
	global_load_lds_dwordx4 v[152:153], off
	s_mov_b32 m0, s62
	v_lshl_add_u64 v[152:153], v[210:211], 0, s[4:5]
	global_load_lds_dwordx4 v[152:153], off
	s_mov_b32 m0, s63
	v_lshl_add_u64 v[152:153], v[212:213], 0, s[4:5]
	global_load_lds_dwordx4 v[152:153], off
	s_waitcnt vmcnt(8) lgkmcnt(0)
	s_setprio 1
	s_barrier
	v_mfma_f32_16x16x32_bf16 v[60:63], v[128:131], v[176:179], v[60:63]
	v_mfma_f32_16x16x32_bf16 v[56:59], v[136:139], v[176:179], v[56:59]
	v_mfma_f32_16x16x32_bf16 v[48:51], v[128:131], v[184:187], v[48:51]
	v_mfma_f32_16x16x32_bf16 v[44:47], v[136:139], v[184:187], v[44:47]
	v_mfma_f32_16x16x32_bf16 v[32:35], v[128:131], v[192:195], v[32:35]
	v_mfma_f32_16x16x32_bf16 v[28:31], v[136:139], v[192:195], v[28:31]
	v_mfma_f32_16x16x32_bf16 v[16:19], v[128:131], v[200:203], v[16:19]
	v_mfma_f32_16x16x32_bf16 v[12:15], v[136:139], v[200:203], v[12:15]
	v_mfma_f32_16x16x32_bf16 v[60:63], v[132:135], v[180:183], v[60:63]
	v_mfma_f32_16x16x32_bf16 v[56:59], v[140:143], v[180:183], v[56:59]
	v_mfma_f32_16x16x32_bf16 v[48:51], v[132:135], v[188:191], v[48:51]
	v_mfma_f32_16x16x32_bf16 v[44:47], v[140:143], v[188:191], v[44:47]
	v_mfma_f32_16x16x32_bf16 v[32:35], v[132:135], v[196:199], v[32:35]
	v_mfma_f32_16x16x32_bf16 v[28:31], v[140:143], v[196:199], v[28:31]
	v_mfma_f32_16x16x32_bf16 v[16:19], v[132:135], v[204:207], v[16:19]
	v_mfma_f32_16x16x32_bf16 v[12:15], v[140:143], v[204:207], v[12:15]
	v_mfma_f32_16x16x32_bf16 v[52:55], v[160:163], v[176:179], v[52:55]
	v_mfma_f32_16x16x32_bf16 v[40:43], v[168:171], v[176:179], v[40:43]
	v_mfma_f32_16x16x32_bf16 v[36:39], v[160:163], v[184:187], v[36:39]
	v_mfma_f32_16x16x32_bf16 v[24:27], v[168:171], v[184:187], v[24:27]
	v_mfma_f32_16x16x32_bf16 v[20:23], v[160:163], v[192:195], v[20:23]
	v_mfma_f32_16x16x32_bf16 v[8:11], v[168:171], v[192:195], v[8:11]
	v_mfma_f32_16x16x32_bf16 v[4:7], v[160:163], v[200:203], v[4:7]
	v_mfma_f32_16x16x32_bf16 v[0:3], v[168:171], v[200:203], v[0:3]
	v_mfma_f32_16x16x32_bf16 v[52:55], v[164:167], v[180:183], v[52:55]
	v_mfma_f32_16x16x32_bf16 v[40:43], v[172:175], v[180:183], v[40:43]
	s_add_i32 s74, s74, 2
	v_mfma_f32_16x16x32_bf16 v[36:39], v[164:167], v[188:191], v[36:39]
	s_add_u32 s72, s72, 0x100
	v_mfma_f32_16x16x32_bf16 v[24:27], v[172:175], v[188:191], v[24:27]
	s_addc_u32 s73, s73, 0
	v_mfma_f32_16x16x32_bf16 v[20:23], v[164:167], v[196:199], v[20:23]
	s_cmpk_gt_u32 s74, 0x55
	v_mfma_f32_16x16x32_bf16 v[8:11], v[172:175], v[196:199], v[8:11]
	s_mov_b64 s[36:37], s[38:39]
	v_mfma_f32_16x16x32_bf16 v[4:7], v[164:167], v[204:207], v[4:7]
	s_setprio 0
	v_mfma_f32_16x16x32_bf16 v[0:3], v[172:175], v[204:207], v[0:3]
	s_barrier
	s_cbranch_scc0 .LBB0_1249
	s_and_b64 vcc, exec, s[8:9]
	s_cbranch_vccz .LBB0_1252
	s_barrier
